# merge 8B store pairs to 16B in fused RMSNorm epilogues; one 16B load for panel stat slots; pipelined LRU scan LDS reads; batched rope loads; sc1 stores in-proj/FFN-in
# speedup vs baseline: 1.0186x; 1.0186x over previous
.LBB0_320:
	s_lshl_b64 s[10:11], s[6:7], 10
	v_lshl_add_u64 v[114:115], v[126:127], 0, s[10:11]
	s_add_u32 s10, s10, 0x1000
	s_addc_u32 s11, s11, 0
	v_lshl_add_u64 v[116:117], v[126:127], 0, s[10:11]
	s_add_u32 s10, s10, 0x1000
	s_addc_u32 s11, s11, 0
	v_lshl_add_u64 v[118:119], v[126:127], 0, s[10:11]
	s_add_u32 s10, s10, 0x1000
	s_addc_u32 s11, s11, 0
	v_lshl_add_u64 v[120:121], v[126:127], 0, s[10:11]
	s_and_b64 s[10:11], s[56:57], exec
	s_cbranch_scc0 .Lscan_bwd
	ds_read_b32 v226, v132 offset:0
	ds_read_b32 v242, v132 offset:4352
	ds_read_b32 v227, v132 offset:272
	ds_read_b32 v243, v132 offset:4624
	ds_read_b32 v228, v132 offset:544
	ds_read_b32 v244, v132 offset:4896
	ds_read_b32 v229, v132 offset:816
	ds_read_b32 v245, v132 offset:5168
	ds_read_b32 v230, v132 offset:1088
	ds_read_b32 v246, v132 offset:5440
	ds_read_b32 v231, v132 offset:1360
	ds_read_b32 v133, v132 offset:5712
	ds_read_b32 v232, v132 offset:1632
	ds_read_b32 v134, v132 offset:5984
	ds_read_b32 v233, v132 offset:1904
	ds_read_b32 v135, v132 offset:6256
	s_waitcnt lgkmcnt(14)
	v_mul_f32_e32 v144, v130, v226
	v_fmac_f32_e32 v242, v129, v226
	v_cvt_pk_bf16_f32 v145, v242, v144
	global_store_dword v[114:115], v145, off
	ds_read_b32 v234, v132 offset:2176
	ds_read_b32 v136, v132 offset:6528
	s_waitcnt lgkmcnt(14)
	v_mul_f32_e32 v130, v144, v227
	v_fmac_f32_e32 v243, v242, v227
	v_cvt_pk_bf16_f32 v146, v243, v130
	global_store_dword v[114:115], v146, off offset:1024
	ds_read_b32 v235, v132 offset:2448
	ds_read_b32 v137, v132 offset:6800
	s_waitcnt lgkmcnt(14)
	v_mul_f32_e32 v144, v130, v228
	v_fmac_f32_e32 v244, v243, v228
	v_cvt_pk_bf16_f32 v145, v244, v144
	global_store_dword v[114:115], v145, off offset:2048
	ds_read_b32 v236, v132 offset:2720
	ds_read_b32 v138, v132 offset:7072
	s_waitcnt lgkmcnt(14)
	v_mul_f32_e32 v130, v144, v229
	v_fmac_f32_e32 v245, v244, v229
	v_cvt_pk_bf16_f32 v146, v245, v130
	global_store_dword v[114:115], v146, off offset:3072
	ds_read_b32 v237, v132 offset:2992
	ds_read_b32 v139, v132 offset:7344
	s_waitcnt lgkmcnt(14)
	v_mul_f32_e32 v144, v130, v230
	v_fmac_f32_e32 v246, v245, v230
	v_cvt_pk_bf16_f32 v145, v246, v144
	global_store_dword v[116:117], v145, off
	ds_read_b32 v238, v132 offset:3264
	ds_read_b32 v140, v132 offset:7616
	s_waitcnt lgkmcnt(14)
	v_mul_f32_e32 v130, v144, v231
	v_fmac_f32_e32 v133, v246, v231
	v_cvt_pk_bf16_f32 v146, v133, v130
	global_store_dword v[116:117], v146, off offset:1024
	ds_read_b32 v239, v132 offset:3536
	ds_read_b32 v141, v132 offset:7888
	s_waitcnt lgkmcnt(14)
	v_mul_f32_e32 v144, v130, v232
	v_fmac_f32_e32 v134, v133, v232
	v_cvt_pk_bf16_f32 v145, v134, v144
	global_store_dword v[116:117], v145, off offset:2048
	ds_read_b32 v240, v132 offset:3808
	ds_read_b32 v142, v132 offset:8160
	s_waitcnt lgkmcnt(14)
	v_mul_f32_e32 v130, v144, v233
	v_fmac_f32_e32 v135, v134, v233
	v_cvt_pk_bf16_f32 v146, v135, v130
	global_store_dword v[116:117], v146, off offset:3072
	ds_read_b32 v241, v132 offset:4080
	ds_read_b32 v143, v132 offset:8432
	s_waitcnt lgkmcnt(14)
	v_mul_f32_e32 v144, v130, v234
	v_fmac_f32_e32 v136, v135, v234
	v_cvt_pk_bf16_f32 v145, v136, v144
	global_store_dword v[118:119], v145, off
	s_waitcnt lgkmcnt(12)
	v_mul_f32_e32 v130, v144, v235
	v_fmac_f32_e32 v137, v136, v235
	v_cvt_pk_bf16_f32 v146, v137, v130
	global_store_dword v[118:119], v146, off offset:1024
	s_waitcnt lgkmcnt(10)
	v_mul_f32_e32 v144, v130, v236
	v_fmac_f32_e32 v138, v137, v236
	v_cvt_pk_bf16_f32 v145, v138, v144
	global_store_dword v[118:119], v145, off offset:2048
	s_waitcnt lgkmcnt(8)
	v_mul_f32_e32 v130, v144, v237
	v_fmac_f32_e32 v139, v138, v237
	v_cvt_pk_bf16_f32 v146, v139, v130
	global_store_dword v[118:119], v146, off offset:3072
	s_waitcnt lgkmcnt(6)
	v_mul_f32_e32 v144, v130, v238
	v_fmac_f32_e32 v140, v139, v238
	v_cvt_pk_bf16_f32 v145, v140, v144
	global_store_dword v[120:121], v145, off
	s_waitcnt lgkmcnt(4)
	v_mul_f32_e32 v130, v144, v239
	v_fmac_f32_e32 v141, v140, v239
	v_cvt_pk_bf16_f32 v146, v141, v130
	global_store_dword v[120:121], v146, off offset:1024
	s_waitcnt lgkmcnt(2)
	v_mul_f32_e32 v144, v130, v240
	v_fmac_f32_e32 v142, v141, v240
	v_cvt_pk_bf16_f32 v145, v142, v144
	global_store_dword v[120:121], v145, off offset:2048
	s_waitcnt lgkmcnt(0)
	v_mul_f32_e32 v130, v144, v241
	v_fmac_f32_e32 v143, v142, v241
	v_cvt_pk_bf16_f32 v146, v143, v130
	global_store_dword v[120:121], v146, off offset:3072
	v_mov_b32_e32 v129, v143
	s_branch .Lscan_done
.Lscan_bwd:
	ds_read_b32 v241, v132 offset:4080
	ds_read_b32 v143, v132 offset:8432
	ds_read_b32 v240, v132 offset:3808
	ds_read_b32 v142, v132 offset:8160
	ds_read_b32 v239, v132 offset:3536
	ds_read_b32 v141, v132 offset:7888
	ds_read_b32 v238, v132 offset:3264
	ds_read_b32 v140, v132 offset:7616
	ds_read_b32 v237, v132 offset:2992
	ds_read_b32 v139, v132 offset:7344
	ds_read_b32 v236, v132 offset:2720
	ds_read_b32 v138, v132 offset:7072
	ds_read_b32 v235, v132 offset:2448
	ds_read_b32 v137, v132 offset:6800
	ds_read_b32 v234, v132 offset:2176
	ds_read_b32 v136, v132 offset:6528
	s_waitcnt lgkmcnt(14)
	v_mul_f32_e32 v144, v130, v241
	v_fmac_f32_e32 v143, v129, v241
	v_cvt_pk_bf16_f32 v145, v143, v144
	global_store_dword v[120:121], v145, off offset:3072
	ds_read_b32 v233, v132 offset:1904
	ds_read_b32 v135, v132 offset:6256
	s_waitcnt lgkmcnt(14)
	v_mul_f32_e32 v130, v144, v240
	v_fmac_f32_e32 v142, v143, v240
	v_cvt_pk_bf16_f32 v146, v142, v130
	global_store_dword v[120:121], v146, off offset:2048
	ds_read_b32 v232, v132 offset:1632
	ds_read_b32 v134, v132 offset:5984
	s_waitcnt lgkmcnt(14)
	v_mul_f32_e32 v144, v130, v239
	v_fmac_f32_e32 v141, v142, v239
	v_cvt_pk_bf16_f32 v145, v141, v144
	global_store_dword v[120:121], v145, off offset:1024
	ds_read_b32 v231, v132 offset:1360
	ds_read_b32 v133, v132 offset:5712
	s_waitcnt lgkmcnt(14)
	v_mul_f32_e32 v130, v144, v238
	v_fmac_f32_e32 v140, v141, v238
	v_cvt_pk_bf16_f32 v146, v140, v130
	global_store_dword v[120:121], v146, off
	ds_read_b32 v230, v132 offset:1088
	ds_read_b32 v246, v132 offset:5440
	s_waitcnt lgkmcnt(14)
	v_mul_f32_e32 v144, v130, v237
	v_fmac_f32_e32 v139, v140, v237
	v_cvt_pk_bf16_f32 v145, v139, v144
	global_store_dword v[118:119], v145, off offset:3072
	ds_read_b32 v229, v132 offset:816
	ds_read_b32 v245, v132 offset:5168
	s_waitcnt lgkmcnt(14)
	v_mul_f32_e32 v130, v144, v236
	v_fmac_f32_e32 v138, v139, v236
	v_cvt_pk_bf16_f32 v146, v138, v130
	global_store_dword v[118:119], v146, off offset:2048
	ds_read_b32 v228, v132 offset:544
	ds_read_b32 v244, v132 offset:4896
	s_waitcnt lgkmcnt(14)
	v_mul_f32_e32 v144, v130, v235
	v_fmac_f32_e32 v137, v138, v235
	v_cvt_pk_bf16_f32 v145, v137, v144
	global_store_dword v[118:119], v145, off offset:1024
	ds_read_b32 v227, v132 offset:272
	ds_read_b32 v243, v132 offset:4624
	s_waitcnt lgkmcnt(14)
	v_mul_f32_e32 v130, v144, v234
	v_fmac_f32_e32 v136, v137, v234
	v_cvt_pk_bf16_f32 v146, v136, v130
	global_store_dword v[118:119], v146, off
	ds_read_b32 v226, v132 offset:0
	ds_read_b32 v242, v132 offset:4352
	s_waitcnt lgkmcnt(14)
	v_mul_f32_e32 v144, v130, v233
	v_fmac_f32_e32 v135, v136, v233
	v_cvt_pk_bf16_f32 v145, v135, v144
	global_store_dword v[116:117], v145, off offset:3072
	s_waitcnt lgkmcnt(12)
	v_mul_f32_e32 v130, v144, v232
	v_fmac_f32_e32 v134, v135, v232
	v_cvt_pk_bf16_f32 v146, v134, v130
	global_store_dword v[116:117], v146, off offset:2048
	s_waitcnt lgkmcnt(10)
	v_mul_f32_e32 v144, v130, v231
	v_fmac_f32_e32 v133, v134, v231
	v_cvt_pk_bf16_f32 v145, v133, v144
	global_store_dword v[116:117], v145, off offset:1024
	s_waitcnt lgkmcnt(8)
	v_mul_f32_e32 v130, v144, v230
	v_fmac_f32_e32 v246, v133, v230
	v_cvt_pk_bf16_f32 v146, v246, v130
	global_store_dword v[116:117], v146, off
	s_waitcnt lgkmcnt(6)
	v_mul_f32_e32 v144, v130, v229
	v_fmac_f32_e32 v245, v246, v229
	v_cvt_pk_bf16_f32 v145, v245, v144
	global_store_dword v[114:115], v145, off offset:3072
	s_waitcnt lgkmcnt(4)
	v_mul_f32_e32 v130, v144, v228
	v_fmac_f32_e32 v244, v245, v228
	v_cvt_pk_bf16_f32 v146, v244, v130
	global_store_dword v[114:115], v146, off offset:2048
	s_waitcnt lgkmcnt(2)
	v_mul_f32_e32 v144, v130, v227
	v_fmac_f32_e32 v243, v244, v227
	v_cvt_pk_bf16_f32 v145, v243, v144
	global_store_dword v[114:115], v145, off offset:1024
	s_waitcnt lgkmcnt(0)
	v_mul_f32_e32 v130, v144, v226
	v_fmac_f32_e32 v242, v243, v226
	v_cvt_pk_bf16_f32 v146, v242, v130
	global_store_dword v[114:115], v146, off
	v_mov_b32_e32 v129, v242
.Lscan_done:
	s_waitcnt lgkmcnt(0)
	s_add_i32 s4, s4, 1
	s_cmp_eq_u32 s4, 4
	s_cbranch_scc0 .LBB0_319
	v_readlane_b32 s4, v252, 55
	s_add_i32 s4, s30, s4
	s_mulk_i32 s4, 0x44
	s_add_i32 s4, s4, s31
	s_ashr_i32 s5, s4, 31
	s_lshl_b64 s[4:5], s[4:5], 11
	v_readlane_b32 s6, v252, 57
	s_add_u32 s4, s6, s4
	v_readlane_b32 s6, v252, 60
	s_addc_u32 s5, s6, s5
	v_lshlrev_b32_e32 v0, 3, v122
	v_lshl_add_u64 v[2:3], s[4:5], 0, v[0:1]
	v_mov_b32_e32 v131, v129
	flat_store_dwordx2 v[2:3], v[130:131]
	s_waitcnt lgkmcnt(0)
	s_barrier
	s_branch .LBB0_260

.LBB0_376:
	s_andn2_b64 vcc, exec, s[4:5]
	s_mov_b64 s[4:5], -1
	s_cbranch_vccnz .LBB0_371
	s_mul_i32 s4, s15, 0xc00
	s_mul_hi_u32 s5, s14, 0xc00
	s_and_b32 s34, s24, 7
	s_add_i32 s5, s5, s4
	s_mul_i32 s4, s14, 0xc00
	s_add_u32 s4, s58, s4
	s_addc_u32 s5, s59, s5
	s_lshl_b32 s6, s34, 7
	s_add_u32 s12, s4, s6
	s_addc_u32 s29, s5, 0
	s_mul_i32 s4, s21, 0x88000
	s_mul_hi_u32 s5, s20, 0x88000
	s_lshl_b32 s6, s24, 4
	s_add_i32 s5, s5, s4
	s_mul_i32 s4, s20, 0x88000
	s_and_b32 s6, s6, 64
	s_or_b32 s4, s4, s6
	s_lshl_b64 s[4:5], s[4:5], 1
	s_load_dwordx2 s[6:7], s[78:79], 0x40
	s_add_u32 s18, s96, s4
	s_addc_u32 s19, s97, s5
	s_add_u32 s4, s48, s4
	s_addc_u32 s5, s49, s5
	v_mbcnt_lo_u32_b32 v0, -1, 0
	v_mbcnt_hi_u32_b32 v0, -1, v0
	s_waitcnt lgkmcnt(0)
	s_add_u32 s36, s6, s10
	v_add_u32_e32 v86, s33, v0
	s_addc_u32 s37, s7, s11
	v_readfirstlane_b32 s25, v86
	s_ashr_i32 s27, s25, 6
	s_lshl_b32 s16, s27, 5
	s_ashr_i32 s17, s16, 31
	s_mul_i32 s6, s27, 0x18000
	s_mul_hi_i32 s7, s16, 0xc00
	s_add_u32 s38, s12, s6
	v_and_b32_e32 v198, 63, v86
	s_addc_u32 s39, s29, s7
	s_lshl_b32 s12, s27, 4
	v_bfe_u32 v192, v86, 2, 4
	v_lshlrev_b32_e32 v182, 8, v198
	v_mov_b32_e32 v183, v1
	s_lshl_b32 s6, s27, 3
	v_and_or_b32 v0, s12, 48, v192
	s_waitcnt vmcnt(0)
	v_lshl_add_u64 v[2:3], s[18:19], 0, v[182:183]
	s_ashr_i32 s7, s6, 31
	v_lshlrev_b32_e32 v0, 8, v0
	v_lshl_add_u64 v[82:83], s[6:7], 1, v[2:3]
	v_lshl_add_u64 v[2:3], s[4:5], 0, v[0:1]
	s_ashr_i32 s4, s25, 3
	s_and_b32 s18, s4, 0xffffffe0
	s_ashr_i32 s19, s18, 31
	v_lshlrev_b32_e32 v199, 3, v86
	s_lshl_b32 s12, s27, 10
	v_and_b32_e32 v202, 24, v199
	s_cmp_lg_u32 0, -1
	v_and_b32_e32 v200, 31, v86
	v_lshl_add_u64 v[2:3], s[18:19], 1, v[2:3]
	v_lshlrev_b32_e32 v0, 1, v202
	s_cselect_b32 s4, 0, 0
	v_lshl_add_u64 v[84:85], v[2:3], 0, v[0:1]
	s_add_i32 s29, s12, s4
	s_mov_b32 s4, m0
	s_mov_b32 m0, s29
	s_nop 0
	global_load_lds_dwordx4 v[82:83], off
	s_mov_b32 m0, s4
	v_mul_u32_u24_e32 v0, 0x600, v200
	v_bfe_u32 v201, v86, 5, 1
	s_add_i32 s30, s29, 0x6000
	s_mov_b32 s4, m0
	s_mov_b32 m0, s30
	s_nop 0
	global_load_lds_dwordx4 v[84:85], off
	s_mov_b32 m0, s4
	v_lshlrev_b32_e32 v0, 1, v0
	s_mov_b64 s[4:5], 0x4000
	v_lshl_or_b32 v0, v201, 4, v0
	v_lshl_add_u64 v[2:3], v[82:83], 0, s[4:5]
	s_add_i32 s4, s29, 0x2000
	s_mov_b32 s5, m0
	s_mov_b32 m0, s4
	s_nop 0
	global_load_lds_dwordx4 v[2:3], off
	s_mov_b32 m0, s5
	v_lshl_add_u64 v[14:15], s[38:39], 0, v[0:1]
	flat_load_dwordx4 v[2:5], v[14:15]
	flat_load_dwordx4 v[6:9], v[14:15] offset:32
	flat_load_dwordx4 v[10:13], v[14:15] offset:64
	s_nop 0
	flat_load_dwordx4 v[14:17], v[14:15] offset:96
	v_and_b32_e32 v0, 32, v86
	v_lshl_add_u64 v[22:23], s[36:37], 0, v[0:1]
	flat_load_dwordx4 v[26:29], v[22:23] offset:128
	flat_load_dwordx4 v[30:33], v[22:23] offset:192
	flat_load_dwordx4 v[34:37], v[22:23] offset:16
	flat_load_dwordx4 v[18:21], v[22:23]
	flat_load_dwordx4 v[38:41], v[22:23] offset:80
	flat_load_dwordx4 v[42:45], v[22:23] offset:64
	flat_load_dwordx4 v[50:53], v[22:23] offset:144
	flat_load_dwordx4 v[54:57], v[22:23] offset:208
	s_andn2_b64 vcc, exec, s[22:23]
	v_lshlrev_b32_e32 v203, 4, v201
	s_waitcnt vmcnt(0) lgkmcnt(0)
	v_mov_b32_e32 v72, v28
	v_and_b32_e32 v23, 0xffff0000, v3
	v_lshlrev_b32_e32 v22, 16, v3
	v_and_b32_e32 v3, 0xffff0000, v2
	v_lshlrev_b32_e32 v2, 16, v2
	v_mul_f32_e32 v0, v3, v3
	v_pk_fma_f32 v[70:71], v[2:3], v[2:3], v[0:1] op_sel_hi:[1,1,0]
	v_mul_f32_e32 v24, v23, v23
	v_pk_fma_f32 v[70:71], v[22:23], v[22:23], v[70:71]
	v_and_b32_e32 v47, 0xffff0000, v5
	v_lshlrev_b32_e32 v46, 16, v5
	v_and_b32_e32 v5, 0xffff0000, v4
	v_lshlrev_b32_e32 v4, 16, v4
	v_pk_add_f32 v[24:25], v[24:25], v[70:71] op_sel_hi:[0,1]
	v_mul_f32_e32 v48, v5, v5
	v_pk_fma_f32 v[24:25], v[4:5], v[4:5], v[24:25]
	v_mul_f32_e32 v62, v47, v47
	v_pk_add_f32 v[24:25], v[48:49], v[24:25] op_sel_hi:[0,1]
	v_pk_fma_f32 v[24:25], v[46:47], v[46:47], v[24:25]
	v_and_b32_e32 v61, 0xffff0000, v7
	v_lshlrev_b32_e32 v60, 16, v7
	v_and_b32_e32 v7, 0xffff0000, v6
	v_lshlrev_b32_e32 v6, 16, v6
	v_pk_add_f32 v[24:25], v[62:63], v[24:25] op_sel_hi:[0,1]
	v_mul_f32_e32 v64, v7, v7
	v_pk_fma_f32 v[24:25], v[6:7], v[6:7], v[24:25]
	v_mul_f32_e32 v66, v61, v61
	v_pk_add_f32 v[24:25], v[64:65], v[24:25] op_sel_hi:[0,1]
	v_pk_fma_f32 v[24:25], v[60:61], v[60:61], v[24:25]
	v_and_b32_e32 v59, 0xffff0000, v9
	v_lshlrev_b32_e32 v58, 16, v9
	v_and_b32_e32 v9, 0xffff0000, v8
	v_lshlrev_b32_e32 v8, 16, v8
	v_pk_add_f32 v[24:25], v[66:67], v[24:25] op_sel_hi:[0,1]
	v_mul_f32_e32 v68, v9, v9
	v_pk_fma_f32 v[24:25], v[8:9], v[8:9], v[24:25]
	v_mul_f32_e32 v0, v59, v59
	v_pk_add_f32 v[24:25], v[68:69], v[24:25] op_sel_hi:[0,1]
	v_pk_fma_f32 v[24:25], v[58:59], v[58:59], v[24:25]
	v_lshlrev_b32_e32 v62, 16, v10
	v_pk_add_f32 v[24:25], v[0:1], v[24:25] op_sel_hi:[0,1]
	v_and_b32_e32 v63, 0xffff0000, v14
	v_and_b32_e32 v65, 0xffff0000, v10
	v_pk_fma_f32 v[24:25], v[62:63], v[62:63], v[24:25]
	v_mul_f32_e32 v0, v65, v65
	v_lshlrev_b32_e32 v64, 16, v14
	v_pk_add_f32 v[24:25], v[0:1], v[24:25] op_sel_hi:[0,1]
	v_lshlrev_b32_e32 v14, 16, v11
	v_lshlrev_b32_e32 v10, 16, v15
	v_and_b32_e32 v15, 0xffff0000, v15
	v_and_b32_e32 v11, 0xffff0000, v11
	v_pk_fma_f32 v[24:25], v[14:15], v[14:15], v[24:25]
	v_mul_f32_e32 v0, v11, v11
	v_pk_add_f32 v[24:25], v[0:1], v[24:25] op_sel_hi:[0,1]
	v_lshlrev_b32_e32 v74, 16, v12
	v_and_b32_e32 v75, 0xffff0000, v16
	v_and_b32_e32 v77, 0xffff0000, v12
	v_pk_fma_f32 v[24:25], v[74:75], v[74:75], v[24:25]
	v_mul_f32_e32 v0, v77, v77
	v_lshlrev_b32_e32 v76, 16, v16
	v_pk_add_f32 v[24:25], v[0:1], v[24:25] op_sel_hi:[0,1]
	v_lshlrev_b32_e32 v16, 16, v13
	v_lshlrev_b32_e32 v12, 16, v17
	v_and_b32_e32 v17, 0xffff0000, v17
	v_and_b32_e32 v13, 0xffff0000, v13
	v_pk_fma_f32 v[24:25], v[16:17], v[16:17], v[24:25]
	v_mul_f32_e32 v0, v13, v13
	v_mov_b32_e32 v66, v64
	v_mov_b32_e32 v67, v63
	v_pk_add_f32 v[24:25], v[0:1], v[24:25] op_sel_hi:[0,1]
	v_pk_fma_f32 v[24:25], v[66:67], v[66:67], v[24:25]
	v_mul_f32_e32 v0, v63, v63
	v_mov_b32_e32 v70, v10
	v_mov_b32_e32 v71, v15
	v_pk_add_f32 v[24:25], v[0:1], v[24:25] op_sel_hi:[0,1]
	v_pk_fma_f32 v[24:25], v[70:71], v[70:71], v[24:25]
	v_mul_f32_e32 v0, v15, v15
	v_mov_b32_e32 v78, v76
	v_mov_b32_e32 v79, v75
	v_pk_add_f32 v[24:25], v[0:1], v[24:25] op_sel_hi:[0,1]
	v_pk_fma_f32 v[24:25], v[78:79], v[78:79], v[24:25]
	v_mul_f32_e32 v0, v75, v75
	v_mov_b32_e32 v80, v12
	v_mov_b32_e32 v81, v17
	v_pk_add_f32 v[24:25], v[0:1], v[24:25] op_sel_hi:[0,1]
	v_pk_fma_f32 v[24:25], v[80:81], v[80:81], v[24:25]
	v_mul_f32_e32 v0, v17, v17
	v_pk_add_f32 v[24:25], v[0:1], v[24:25] op_sel_hi:[0,1]
	v_mov_b32_e32 v0, v24
	s_nop 1
	v_permlane32_swap_b32_e32 v24, v0
	v_add_f32_e32 v0, v24, v0
	v_fmamk_f32 v0, v0, 0x3c800000, v223
	v_rsq_f32_e32 v0, v0
	v_mov_b32_e32 v68, v26
	v_mov_b32_e32 v69, v31
	v_mov_b32_e32 v26, v30
	v_pk_mul_f32 v[18:19], v[18:19], v[0:1] op_sel_hi:[1,0]
	v_mov_b32_e32 v28, v32
	v_pk_mul_f32 v[24:25], v[18:19], v[2:3]
	v_pk_mul_f32 v[2:3], v[20:21], v[0:1] op_sel_hi:[1,0]
	v_mov_b32_e32 v88, v50
	v_pk_mul_f32 v[22:23], v[2:3], v[22:23]
	v_pk_mul_f32 v[2:3], v[0:1], v[34:35] op_sel_hi:[0,1]
	v_pk_mul_f32 v[20:21], v[2:3], v[4:5]
	v_pk_mul_f32 v[2:3], v[0:1], v[36:37] op_sel_hi:[0,1]
	v_pk_mul_f32 v[18:19], v[2:3], v[46:47]
	v_pk_mul_f32 v[2:3], v[0:1], v[42:43] op_sel_hi:[0,1]
	v_pk_mul_f32 v[48:49], v[2:3], v[6:7]
	v_pk_mul_f32 v[2:3], v[0:1], v[44:45] op_sel_hi:[0,1]
	v_pk_mul_f32 v[46:47], v[2:3], v[60:61]
	v_pk_mul_f32 v[2:3], v[0:1], v[38:39] op_sel_hi:[0,1]
	v_pk_mul_f32 v[44:45], v[2:3], v[8:9]
	v_pk_mul_f32 v[2:3], v[0:1], v[40:41] op_sel_hi:[0,1]
	v_mov_b32_e32 v50, v54
	v_pk_mul_f32 v[42:43], v[2:3], v[58:59]
	v_pk_mul_f32 v[2:3], v[0:1], v[68:69] op_sel_hi:[0,1]
	v_pk_mul_f32 v[4:5], v[0:1], v[26:27] op_sel_hi:[0,1]
	v_pk_mul_f32 v[8:9], v[0:1], v[28:29] op_sel_hi:[0,1]
	v_pk_mul_f32 v[28:29], v[0:1], v[50:51] op_sel_hi:[0,1]
	v_mov_b32_e32 v34, v52
	v_mov_b32_e32 v35, v57
	v_pk_mul_f32 v[50:51], v[4:5], v[64:65]
	v_pk_mul_f32 v[64:65], v[2:3], v[62:63]
	v_pk_mul_f32 v[2:3], v[0:1], v[32:33] op_sel_hi:[0,1]
	v_mov_b32_e32 v73, v33
	v_mov_b32_e32 v89, v55
	v_pk_mul_f32 v[58:59], v[0:1], v[34:35] op_sel_hi:[0,1]
	v_mov_b32_e32 v52, v56
	v_pk_mul_f32 v[34:35], v[2:3], v[70:71]
	v_pk_mul_f32 v[2:3], v[0:1], v[54:55] op_sel_hi:[0,1]
	v_pk_mul_f32 v[6:7], v[0:1], v[72:73] op_sel_hi:[0,1]
	v_pk_mul_f32 v[26:27], v[0:1], v[88:89] op_sel_hi:[0,1]
	v_pk_mul_f32 v[40:41], v[0:1], v[52:53] op_sel_hi:[0,1]
	v_pk_mul_f32 v[30:31], v[0:1], v[30:31] op_sel_hi:[0,1]
	v_pk_mul_f32 v[36:37], v[2:3], v[78:79]
	v_pk_mul_f32 v[2:3], v[0:1], v[56:57] op_sel_hi:[0,1]
	v_cndmask_b32_e64 v0, 0, 1, s[22:23]
	v_pk_mul_f32 v[38:39], v[30:31], v[66:67]
	v_pk_mul_f32 v[52:53], v[8:9], v[10:11]
	v_pk_mul_f32 v[62:63], v[6:7], v[14:15]
	v_pk_mul_f32 v[54:55], v[28:29], v[76:77]
	v_pk_mul_f32 v[60:61], v[26:27], v[74:75]
	v_pk_mul_f32 v[56:57], v[40:41], v[12:13]
	v_pk_mul_f32 v[40:41], v[2:3], v[80:81]
	v_pk_mul_f32 v[58:59], v[58:59], v[16:17]
	v_cmp_ne_u32_e64 s[4:5], 1, v0
	s_cbranch_vccnz .LBB0_379
	s_and_b32 s22, s14, 0xfff
	s_add_i32 s22, s16, s22
	v_add_u32_e32 v0, s22, v200
	v_ashrrev_i32_e32 v8, 1, v0
	s_movk_i32 s22, 0xffe0
	v_and_or_b32 v8, v8, s22, v203
	v_readlane_b32 s36, v252, 40
	v_ashrrev_i32_e32 v9, 31, v8
	v_readlane_b32 s37, v252, 41
	v_lshlrev_b32_e32 v0, 5, v0
	s_movk_i32 s22, 0x7e0
	v_lshl_add_u64 v[14:15], v[8:9], 2, s[36:37]
	global_load_dwordx4 v[226:229], v[14:15], off
	global_load_dwordx4 v[230:233], v[14:15], off offset:16
	global_load_dwordx4 v[234:237], v[14:15], off offset:32
	global_load_dwordx4 v[238:241], v[14:15], off offset:48
	v_and_or_b32 v0, v0, s22, v203
	v_lshlrev_b32_e32 v0, 2, v0
	v_lshl_add_u64 v[218:219], s[36:37], 0, v[0:1]
	global_load_dwordx4 v[242:245], v[218:219], off
	global_load_dwordx4 v[246:249], v[218:219], off offset:16
	v_mov_b32_e32 v12, v64
	v_mov_b32_e32 v13, v51
	v_mov_b32_e32 v4, v62
	v_mov_b32_e32 v5, v53
	v_mov_b32_e32 v2, v60
	v_mov_b32_e32 v3, v55
	v_mov_b32_e32 v6, v58
	v_mov_b32_e32 v7, v57
	s_waitcnt vmcnt(5)
	v_mov_b32_e32 v8, v226
	v_mov_b32_e32 v9, v227
	v_mov_b32_e32 v10, v228
	v_mov_b32_e32 v11, v229
	global_load_dwordx4 v[226:229], v[218:219], off offset:32
	v_mov_b32_e32 v17, v10
	v_mov_b32_e32 v10, v9
	v_mov_b32_e32 v16, v8
	v_pk_mul_f32 v[8:9], v[24:25], v[10:11]
	v_pk_mul_f32 v[10:11], v[48:49], v[10:11]
	v_pk_fma_f32 v[48:49], v[48:49], v[16:17], v[8:9]
	v_pk_fma_f32 v[24:25], v[24:25], v[16:17], v[10:11] neg_lo:[0,0,1] neg_hi:[0,0,1]
	s_waitcnt vmcnt(5)
	v_mov_b32_e32 v8, v230
	v_mov_b32_e32 v9, v231
	v_mov_b32_e32 v10, v232
	v_mov_b32_e32 v11, v233
	global_load_dwordx4 v[230:233], v[218:219], off offset:48
	v_mov_b32_e32 v17, v10
	v_mov_b32_e32 v10, v9
	v_mov_b32_e32 v16, v8
	v_pk_mul_f32 v[8:9], v[22:23], v[10:11]
	v_pk_mul_f32 v[10:11], v[46:47], v[10:11]
	v_pk_fma_f32 v[46:47], v[46:47], v[16:17], v[8:9]
	v_pk_fma_f32 v[22:23], v[22:23], v[16:17], v[10:11] neg_lo:[0,0,1] neg_hi:[0,0,1]
	s_waitcnt vmcnt(5)
	v_mov_b32_e32 v8, v234
	v_mov_b32_e32 v9, v235
	v_mov_b32_e32 v10, v236
	v_mov_b32_e32 v11, v237
	v_mov_b32_e32 v17, v10
	v_mov_b32_e32 v10, v9
	v_mov_b32_e32 v16, v8
	v_pk_mul_f32 v[8:9], v[20:21], v[10:11]
	v_pk_mul_f32 v[10:11], v[44:45], v[10:11]
	v_pk_fma_f32 v[44:45], v[44:45], v[16:17], v[8:9]
	v_pk_fma_f32 v[20:21], v[20:21], v[16:17], v[10:11] neg_lo:[0,0,1] neg_hi:[0,0,1]
	s_waitcnt vmcnt(4)
	v_mov_b32_e32 v8, v238
	v_mov_b32_e32 v9, v239
	v_mov_b32_e32 v10, v240
	v_mov_b32_e32 v11, v241
	v_mov_b32_e32 v15, v10
	v_mov_b32_e32 v10, v9
	v_mov_b32_e32 v14, v8
	v_pk_mul_f32 v[8:9], v[18:19], v[10:11]
	v_pk_mul_f32 v[10:11], v[42:43], v[10:11]
	v_pk_fma_f32 v[42:43], v[42:43], v[14:15], v[8:9]
	v_pk_fma_f32 v[18:19], v[18:19], v[14:15], v[10:11] neg_lo:[0,0,1] neg_hi:[0,0,1]
	v_lshl_add_u64 v[14:15], s[36:37], 0, v[0:1]
	s_waitcnt vmcnt(3)
	v_mov_b32_e32 v8, v242
	v_mov_b32_e32 v9, v243
	v_mov_b32_e32 v10, v244
	v_mov_b32_e32 v11, v245
	v_mov_b32_e32 v28, v9
	v_mov_b32_e32 v29, v11
	v_mov_b32_e32 v16, v9
	v_mov_b32_e32 v26, v8
	v_mov_b32_e32 v27, v11
	v_pk_mul_f32 v[28:29], v[38:39], v[28:29]
	v_mov_b32_e32 v9, v10
	v_mov_b32_e32 v17, v10
	v_pk_mul_f32 v[26:27], v[50:51], v[26:27]
	v_pk_fma_f32 v[50:51], v[12:13], v[8:9], v[28:29] neg_lo:[0,0,1] neg_hi:[0,0,1]
	v_pk_fma_f32 v[38:39], v[64:65], v[16:17], v[26:27]
	v_mov_b32_e32 v64, v50
	s_waitcnt vmcnt(2)
	v_mov_b32_e32 v8, v246
	v_mov_b32_e32 v9, v247
	v_mov_b32_e32 v10, v248
	v_mov_b32_e32 v11, v249
	v_mov_b32_e32 v26, v9
	v_mov_b32_e32 v27, v11
	v_mov_b32_e32 v12, v9
	v_mov_b32_e32 v16, v8
	v_mov_b32_e32 v17, v11
	v_pk_mul_f32 v[26:27], v[34:35], v[26:27]
	v_mov_b32_e32 v9, v10
	v_mov_b32_e32 v13, v10
	v_pk_mul_f32 v[16:17], v[52:53], v[16:17]
	v_pk_fma_f32 v[52:53], v[4:5], v[8:9], v[26:27] neg_lo:[0,0,1] neg_hi:[0,0,1]
	v_pk_fma_f32 v[34:35], v[62:63], v[12:13], v[16:17]
	v_mov_b32_e32 v62, v52
	s_waitcnt vmcnt(1)
	v_mov_b32_e32 v8, v226
	v_mov_b32_e32 v9, v227
	v_mov_b32_e32 v10, v228
	v_mov_b32_e32 v11, v229
	v_mov_b32_e32 v12, v8
	v_mov_b32_e32 v13, v11
	v_mov_b32_e32 v16, v9
	v_mov_b32_e32 v17, v11
	v_mov_b32_e32 v4, v9
	v_mov_b32_e32 v5, v10
	v_pk_mul_f32 v[12:13], v[54:55], v[12:13]
	v_pk_mul_f32 v[16:17], v[36:37], v[16:17]
	v_mov_b32_e32 v9, v10
	v_pk_fma_f32 v[54:55], v[2:3], v[8:9], v[16:17] neg_lo:[0,0,1] neg_hi:[0,0,1]
	v_pk_fma_f32 v[36:37], v[60:61], v[4:5], v[12:13]
	v_mov_b32_e32 v60, v54
	s_waitcnt vmcnt(0)
	v_mov_b32_e32 v2, v230
	v_mov_b32_e32 v3, v231
	v_mov_b32_e32 v4, v232
	v_mov_b32_e32 v5, v233
	v_mov_b32_e32 v12, v3
	v_mov_b32_e32 v13, v5
	v_mov_b32_e32 v8, v3
	v_mov_b32_e32 v10, v2
	v_mov_b32_e32 v11, v5
	v_pk_mul_f32 v[12:13], v[40:41], v[12:13]
	v_mov_b32_e32 v3, v4
	v_mov_b32_e32 v9, v4
	v_pk_mul_f32 v[10:11], v[56:57], v[10:11]
	v_pk_fma_f32 v[56:57], v[6:7], v[2:3], v[12:13] neg_lo:[0,0,1] neg_hi:[0,0,1]
	v_pk_fma_f32 v[40:41], v[58:59], v[8:9], v[10:11]
	v_mov_b32_e32 v58, v56

.LBB0_662:
	v_readlane_b32 s4, v255, 7
	s_lshl_b32 s12, s4, 5
	v_and_or_b32 v0, v216, 31, s12
	v_lshl_add_u32 v216, s20, 8, v0
	v_lshl_add_u32 v249, v0, 2, 0
	s_and_saveexec_b64 s[4:5], s[6:7]
	s_cbranch_execz .LBB0_664
	v_readlane_b32 s16, v254, 59
	v_ashrrev_i32_e32 v217, 31, v216
	v_readlane_b32 s17, v254, 60
	s_mov_b32 s15, 0x800000
	s_nop 0
	v_lshl_add_u64 v[230:231], v[216:217], 4, s[16:17]
	global_load_dwordx4 v[242:245], v[230:231], off sc1
	s_waitcnt vmcnt(0)
	v_add_f32_e32 v0, 0, v242
	v_add_f32_e32 v0, v0, v243
	v_add_f32_e32 v0, v0, v244
	v_add_f32_e32 v0, v0, v245
	v_fmamk_f32 v0, v0, 0x3a800000, v223
	v_cmp_gt_f32_e32 vcc, s15, v0
	v_mul_f32_e32 v217, 0x4b800000, v0
	s_nop 0
	v_cndmask_b32_e32 v0, v0, v217, vcc
	v_rsq_f32_e32 v0, v0
	s_nop 0
	v_mul_f32_e32 v217, 0x45800000, v0
	v_cndmask_b32_e32 v0, v0, v217, vcc
	ds_write_b32 v249, v0 offset:8192

.LBB0_684:
	s_or_b64 exec, exec, s[4:5]
	v_readlane_b32 s4, v253, 4
	s_waitcnt lgkmcnt(0)
	v_lshl_add_u64 v[162:163], v[214:215], 0, s[22:23]
	v_readlane_b32 s5, v253, 5
	v_cvt_pk_bf16_f32 v234, v126, v127
	v_cvt_pk_bf16_f32 v235, v128, v129
	v_readlane_b32 s15, v255, 4
	v_readlane_b32 s16, v255, 3
	v_lshl_add_u64 v[162:163], v[162:163], 1, s[4:5]
	v_cvt_pk_bf16_f32 v236, v122, v123
	v_cvt_pk_bf16_f32 v237, v124, v125
	global_store_dwordx4 v[162:163], v[234:237], off
	v_cvt_pk_bf16_f32 v238, v118, v119
	v_cvt_pk_bf16_f32 v239, v120, v121
	s_mov_b32 s4, 0x8000
	v_cvt_pk_bf16_f32 v240, v110, v111
	v_cvt_pk_bf16_f32 v241, v112, v113
	global_store_dwordx4 v[162:163], v[238:241], off offset:256
	v_add_co_u32_e32 v166, vcc, s4, v162
	v_cvt_pk_bf16_f32 v234, v114, v115
	v_cvt_pk_bf16_f32 v235, v116, v117
	s_mov_b32 s4, 0x10000
	s_nop 0
	v_addc_co_u32_e32 v167, vcc, 0, v163, vcc
	v_cvt_pk_bf16_f32 v236, v106, v107
	v_cvt_pk_bf16_f32 v237, v108, v109
	global_store_dwordx4 v[166:167], v[234:237], off
	v_cvt_pk_bf16_f32 v238, v102, v103
	v_cvt_pk_bf16_f32 v239, v104, v105
	v_cvt_pk_bf16_f32 v240, v94, v95
	v_cvt_pk_bf16_f32 v241, v96, v97
	global_store_dwordx4 v[166:167], v[238:241], off offset:256
	v_add_co_u32_e32 v166, vcc, s4, v162
	v_cvt_pk_bf16_f32 v234, v98, v99
	v_cvt_pk_bf16_f32 v235, v100, v101
	s_mov_b32 s4, 0x18000
	s_nop 0
	v_addc_co_u32_e32 v167, vcc, 0, v163, vcc
	v_cvt_pk_bf16_f32 v236, v90, v91
	v_cvt_pk_bf16_f32 v237, v92, v93
	global_store_dwordx4 v[166:167], v[234:237], off
	v_cvt_pk_bf16_f32 v238, v86, v87
	v_cvt_pk_bf16_f32 v239, v88, v89
	v_cvt_pk_bf16_f32 v240, v78, v79
	v_cvt_pk_bf16_f32 v241, v80, v81
	global_store_dwordx4 v[166:167], v[238:241], off offset:256
	v_add_co_u32_e32 v166, vcc, s4, v162
	v_cvt_pk_bf16_f32 v234, v82, v83
	v_cvt_pk_bf16_f32 v235, v84, v85
	s_mov_b32 s4, 0x40000
	s_nop 0
	v_addc_co_u32_e32 v167, vcc, 0, v163, vcc
	v_cvt_pk_bf16_f32 v236, v74, v75
	v_cvt_pk_bf16_f32 v237, v76, v77
	global_store_dwordx4 v[166:167], v[234:237], off
	v_cvt_pk_bf16_f32 v238, v70, v71
	v_cvt_pk_bf16_f32 v239, v72, v73
	v_cvt_pk_bf16_f32 v240, v66, v67
	v_cvt_pk_bf16_f32 v241, v68, v69
	global_store_dwordx4 v[166:167], v[238:241], off offset:256
	v_add_co_u32_e32 v166, vcc, s4, v162
	v_cvt_pk_bf16_f32 v234, v62, v63
	v_cvt_pk_bf16_f32 v235, v64, v65
	s_mov_b32 s4, 0x48000
	s_nop 0
	v_addc_co_u32_e32 v167, vcc, 0, v163, vcc
	v_cvt_pk_bf16_f32 v236, v58, v59
	v_cvt_pk_bf16_f32 v237, v60, v61
	global_store_dwordx4 v[166:167], v[234:237], off
	v_cvt_pk_bf16_f32 v238, v54, v55
	v_cvt_pk_bf16_f32 v239, v56, v57
	v_cvt_pk_bf16_f32 v240, v46, v47
	v_cvt_pk_bf16_f32 v241, v48, v49
	global_store_dwordx4 v[166:167], v[238:241], off offset:256
	v_add_co_u32_e32 v166, vcc, s4, v162
	v_cvt_pk_bf16_f32 v234, v50, v51
	v_cvt_pk_bf16_f32 v235, v52, v53
	s_mov_b32 s4, 0x50000
	s_nop 0
	v_addc_co_u32_e32 v167, vcc, 0, v163, vcc
	v_cvt_pk_bf16_f32 v236, v42, v43
	v_cvt_pk_bf16_f32 v237, v44, v45
	global_store_dwordx4 v[166:167], v[234:237], off
	v_cvt_pk_bf16_f32 v238, v38, v39
	v_cvt_pk_bf16_f32 v239, v40, v41
	v_cvt_pk_bf16_f32 v240, v30, v31
	v_cvt_pk_bf16_f32 v241, v32, v33
	global_store_dwordx4 v[166:167], v[238:241], off offset:256
	v_add_co_u32_e32 v166, vcc, s4, v162
	v_cvt_pk_bf16_f32 v234, v34, v35
	v_cvt_pk_bf16_f32 v235, v36, v37
	s_mov_b32 s4, 0x58000
	s_nop 0
	v_addc_co_u32_e32 v167, vcc, 0, v163, vcc
	v_cvt_pk_bf16_f32 v236, v26, v27
	v_cvt_pk_bf16_f32 v237, v28, v29
	global_store_dwordx4 v[166:167], v[234:237], off
	v_cvt_pk_bf16_f32 v238, v22, v23
	v_cvt_pk_bf16_f32 v239, v24, v25
	v_cvt_pk_bf16_f32 v240, v14, v15
	v_cvt_pk_bf16_f32 v241, v16, v17
	global_store_dwordx4 v[166:167], v[238:241], off offset:256
	v_add_co_u32_e32 v162, vcc, s4, v162
	v_cvt_pk_bf16_f32 v234, v18, v19
	v_cvt_pk_bf16_f32 v235, v20, v21
	s_add_u32 s4, s15, s24
	s_nop 0
	v_addc_co_u32_e32 v163, vcc, 0, v163, vcc
	v_cvt_pk_bf16_f32 v236, v10, v11
	v_cvt_pk_bf16_f32 v237, v12, v13
	global_store_dwordx4 v[162:163], v[234:237], off
	v_cvt_pk_bf16_f32 v238, v6, v7
	v_cvt_pk_bf16_f32 v239, v8, v9
	v_cvt_pk_bf16_f32 v240, v2, v3
	v_cvt_pk_bf16_f32 v241, v4, v5
	global_store_dwordx4 v[162:163], v[238:241], off offset:256
	s_addc_u32 s5, s16, s25
	s_mov_b32 s12, 0x40001
	s_branch .LBB0_686

.LBB0_704:
	s_and_saveexec_b64 s[4:5], s[6:7]
	s_cbranch_execz .LBB0_706
	v_ashrrev_i32_e32 v217, 31, v216
	v_lshl_add_u64 v[162:163], v[216:217], 4, s[34:35]
	global_load_dwordx4 v[242:245], v[162:163], off sc1
	s_mov_b32 s6, 0x800000
	s_waitcnt vmcnt(0)
	v_add_f32_e32 v164, 0, v242
	v_add_f32_e32 v164, v164, v243
	v_add_f32_e32 v164, v164, v244
	v_add_f32_e32 v162, v164, v245
	v_fmamk_f32 v162, v162, 0x3a800000, v223
	v_cmp_gt_f32_e32 vcc, s6, v162
	v_mul_f32_e32 v163, 0x4b800000, v162
	s_nop 0
	v_cndmask_b32_e32 v162, v162, v163, vcc
	v_rsq_f32_e32 v162, v162
	s_nop 0
	v_mul_f32_e32 v163, 0x45800000, v162
	v_cndmask_b32_e32 v162, v162, v163, vcc
	ds_write_b32 v249, v162 offset:8192
.LBB0_706:
	s_or_b64 exec, exec, s[4:5]
	s_waitcnt vmcnt(0) lgkmcnt(0)
	s_barrier
	ds_read_b32 v164, v0 offset:8192
	s_lshl_b64 s[4:5], s[22:23], 1
	v_readlane_b32 s6, v254, 8
	s_add_u32 s4, s6, s4
	v_readlane_b32 s6, v254, 9
	s_addc_u32 s5, s6, s5
	s_waitcnt lgkmcnt(0)
	v_pk_mul_f32 v[126:127], v[126:127], v[164:165] op_sel_hi:[1,0]
	v_pk_mul_f32 v[122:123], v[122:123], v[164:165] op_sel_hi:[1,0]
	v_pk_mul_f32 v[118:119], v[118:119], v[164:165] op_sel_hi:[1,0]
	v_pk_mul_f32 v[110:111], v[110:111], v[164:165] op_sel_hi:[1,0]
	v_lshl_add_u64 v[162:163], v[214:215], 1, s[4:5]
	v_pk_mul_f32 v[128:129], v[128:129], v[164:165] op_sel_hi:[1,0]
	v_pk_fma_f32 v[126:127], v[154:155], v[126:127], v[158:159]
	v_pk_mul_f32 v[124:125], v[124:125], v[164:165] op_sel_hi:[1,0]
	v_pk_fma_f32 v[122:123], v[146:147], v[122:123], v[150:151]
	v_pk_mul_f32 v[120:121], v[120:121], v[164:165] op_sel_hi:[1,0]
	v_pk_fma_f32 v[118:119], v[138:139], v[118:119], v[142:143]
	v_pk_mul_f32 v[112:113], v[112:113], v[164:165] op_sel_hi:[1,0]
	v_pk_fma_f32 v[110:111], v[130:131], v[110:111], v[134:135]
	v_pk_fma_f32 v[128:129], v[156:157], v[128:129], v[160:161]
	v_cvt_pk_bf16_f32 v234, v126, v127
	v_pk_fma_f32 v[124:125], v[148:149], v[124:125], v[152:153]
	v_cvt_pk_bf16_f32 v235, v128, v129
	v_cvt_pk_bf16_f32 v236, v122, v123
	v_cvt_pk_bf16_f32 v237, v124, v125
	global_store_dwordx4 v[162:163], v[234:237], off
	v_pk_fma_f32 v[120:121], v[140:141], v[120:121], v[144:145]
	v_cvt_pk_bf16_f32 v238, v118, v119
	v_pk_fma_f32 v[112:113], v[132:133], v[112:113], v[136:137]
	v_cvt_pk_bf16_f32 v239, v120, v121
	v_cvt_pk_bf16_f32 v240, v110, v111
	v_cvt_pk_bf16_f32 v241, v112, v113
	global_store_dwordx4 v[162:163], v[238:241], off offset:256
	ds_read_b32 v110, v0 offset:8256
	s_mov_b32 s4, 0x8000
	s_waitcnt lgkmcnt(0)
	v_pk_mul_f32 v[112:113], v[116:117], v[110:111] op_sel_hi:[1,0]
	v_pk_mul_f32 v[114:115], v[114:115], v[110:111] op_sel_hi:[1,0]
	v_pk_fma_f32 v[112:113], v[156:157], v[112:113], v[160:161]
	v_pk_fma_f32 v[114:115], v[154:155], v[114:115], v[158:159]
	v_pk_mul_f32 v[106:107], v[106:107], v[110:111] op_sel_hi:[1,0]
	v_cvt_pk_bf16_f32 v234, v114, v115
	v_cvt_pk_bf16_f32 v235, v112, v113
	v_add_co_u32_e32 v112, vcc, s4, v162
	v_pk_mul_f32 v[102:103], v[102:103], v[110:111] op_sel_hi:[1,0]
	v_pk_mul_f32 v[94:95], v[94:95], v[110:111] op_sel_hi:[1,0]
	v_addc_co_u32_e32 v113, vcc, 0, v163, vcc
	v_pk_mul_f32 v[108:109], v[108:109], v[110:111] op_sel_hi:[1,0]
	v_pk_fma_f32 v[106:107], v[146:147], v[106:107], v[150:151]
	v_pk_mul_f32 v[104:105], v[104:105], v[110:111] op_sel_hi:[1,0]
	v_pk_fma_f32 v[102:103], v[138:139], v[102:103], v[142:143]
	v_pk_mul_f32 v[96:97], v[96:97], v[110:111] op_sel_hi:[1,0]
	v_pk_fma_f32 v[94:95], v[130:131], v[94:95], v[134:135]
	v_pk_fma_f32 v[108:109], v[148:149], v[108:109], v[152:153]
	v_cvt_pk_bf16_f32 v236, v106, v107
	v_pk_fma_f32 v[104:105], v[140:141], v[104:105], v[144:145]
	v_cvt_pk_bf16_f32 v237, v108, v109
	global_store_dwordx4 v[112:113], v[234:237], off
	v_cvt_pk_bf16_f32 v238, v102, v103
	v_cvt_pk_bf16_f32 v239, v104, v105
	v_pk_fma_f32 v[96:97], v[132:133], v[96:97], v[136:137]
	v_cvt_pk_bf16_f32 v240, v94, v95
	s_mov_b32 s4, 0x10000
	v_cvt_pk_bf16_f32 v241, v96, v97
	global_store_dwordx4 v[112:113], v[238:241], off offset:256
	ds_read_b32 v94, v0 offset:8320
	s_waitcnt lgkmcnt(0)
	v_pk_mul_f32 v[96:97], v[100:101], v[94:95] op_sel_hi:[1,0]
	v_pk_mul_f32 v[98:99], v[98:99], v[94:95] op_sel_hi:[1,0]
	v_pk_fma_f32 v[96:97], v[156:157], v[96:97], v[160:161]
	v_pk_fma_f32 v[98:99], v[154:155], v[98:99], v[158:159]
	v_pk_mul_f32 v[90:91], v[90:91], v[94:95] op_sel_hi:[1,0]
	v_cvt_pk_bf16_f32 v234, v98, v99
	v_cvt_pk_bf16_f32 v235, v96, v97
	v_add_co_u32_e32 v96, vcc, s4, v162
	v_pk_mul_f32 v[86:87], v[86:87], v[94:95] op_sel_hi:[1,0]
	v_pk_mul_f32 v[78:79], v[78:79], v[94:95] op_sel_hi:[1,0]
	v_addc_co_u32_e32 v97, vcc, 0, v163, vcc
	v_pk_mul_f32 v[92:93], v[92:93], v[94:95] op_sel_hi:[1,0]
	v_pk_fma_f32 v[90:91], v[146:147], v[90:91], v[150:151]
	v_pk_mul_f32 v[88:89], v[88:89], v[94:95] op_sel_hi:[1,0]
	v_pk_fma_f32 v[86:87], v[138:139], v[86:87], v[142:143]
	v_pk_mul_f32 v[80:81], v[80:81], v[94:95] op_sel_hi:[1,0]
	v_pk_fma_f32 v[78:79], v[130:131], v[78:79], v[134:135]
	v_pk_fma_f32 v[92:93], v[148:149], v[92:93], v[152:153]
	v_cvt_pk_bf16_f32 v236, v90, v91
	v_pk_fma_f32 v[88:89], v[140:141], v[88:89], v[144:145]
	v_cvt_pk_bf16_f32 v237, v92, v93
	global_store_dwordx4 v[96:97], v[234:237], off
	v_cvt_pk_bf16_f32 v238, v86, v87
	v_cvt_pk_bf16_f32 v239, v88, v89
	v_pk_fma_f32 v[80:81], v[132:133], v[80:81], v[136:137]
	v_cvt_pk_bf16_f32 v240, v78, v79
	s_mov_b32 s4, 0x18000
	v_cvt_pk_bf16_f32 v241, v80, v81
	global_store_dwordx4 v[96:97], v[238:241], off offset:256
	ds_read_b32 v78, v0 offset:8384
	s_waitcnt lgkmcnt(0)
	v_pk_mul_f32 v[80:81], v[84:85], v[78:79] op_sel_hi:[1,0]
	v_pk_mul_f32 v[82:83], v[82:83], v[78:79] op_sel_hi:[1,0]
	v_pk_fma_f32 v[80:81], v[156:157], v[80:81], v[160:161]
	v_pk_fma_f32 v[82:83], v[154:155], v[82:83], v[158:159]
	v_pk_mul_f32 v[74:75], v[74:75], v[78:79] op_sel_hi:[1,0]
	v_cvt_pk_bf16_f32 v234, v82, v83
	v_cvt_pk_bf16_f32 v235, v80, v81
	v_add_co_u32_e32 v80, vcc, s4, v162
	v_pk_mul_f32 v[70:71], v[70:71], v[78:79] op_sel_hi:[1,0]
	v_pk_mul_f32 v[66:67], v[66:67], v[78:79] op_sel_hi:[1,0]
	v_addc_co_u32_e32 v81, vcc, 0, v163, vcc
	v_pk_mul_f32 v[76:77], v[76:77], v[78:79] op_sel_hi:[1,0]
	v_pk_fma_f32 v[74:75], v[146:147], v[74:75], v[150:151]
	v_pk_mul_f32 v[72:73], v[72:73], v[78:79] op_sel_hi:[1,0]
	v_pk_fma_f32 v[70:71], v[138:139], v[70:71], v[142:143]
	v_pk_mul_f32 v[68:69], v[68:69], v[78:79] op_sel_hi:[1,0]
	v_pk_fma_f32 v[66:67], v[130:131], v[66:67], v[134:135]
	v_pk_fma_f32 v[76:77], v[148:149], v[76:77], v[152:153]
	v_cvt_pk_bf16_f32 v236, v74, v75
	v_pk_fma_f32 v[72:73], v[140:141], v[72:73], v[144:145]
	v_cvt_pk_bf16_f32 v237, v76, v77
	global_store_dwordx4 v[80:81], v[234:237], off
	v_cvt_pk_bf16_f32 v238, v70, v71
	v_cvt_pk_bf16_f32 v239, v72, v73
	v_pk_fma_f32 v[68:69], v[132:133], v[68:69], v[136:137]
	v_cvt_pk_bf16_f32 v240, v66, v67
	s_mov_b32 s4, 0x40000
	v_cvt_pk_bf16_f32 v241, v68, v69
	global_store_dwordx4 v[80:81], v[238:241], off offset:256
	ds_read_b32 v66, v0 offset:8704
	s_waitcnt lgkmcnt(0)
	v_pk_mul_f32 v[64:65], v[64:65], v[66:67] op_sel_hi:[1,0]
	v_pk_mul_f32 v[62:63], v[62:63], v[66:67] op_sel_hi:[1,0]
	v_pk_fma_f32 v[64:65], v[156:157], v[64:65], v[160:161]
	v_pk_fma_f32 v[62:63], v[154:155], v[62:63], v[158:159]
	v_pk_mul_f32 v[58:59], v[58:59], v[66:67] op_sel_hi:[1,0]
	v_cvt_pk_bf16_f32 v234, v62, v63
	v_cvt_pk_bf16_f32 v235, v64, v65
	v_add_co_u32_e32 v64, vcc, s4, v162
	v_pk_mul_f32 v[54:55], v[54:55], v[66:67] op_sel_hi:[1,0]
	v_pk_mul_f32 v[46:47], v[46:47], v[66:67] op_sel_hi:[1,0]
	v_addc_co_u32_e32 v65, vcc, 0, v163, vcc
	v_pk_mul_f32 v[60:61], v[60:61], v[66:67] op_sel_hi:[1,0]
	v_pk_fma_f32 v[58:59], v[146:147], v[58:59], v[150:151]
	v_pk_mul_f32 v[56:57], v[56:57], v[66:67] op_sel_hi:[1,0]
	v_pk_fma_f32 v[54:55], v[138:139], v[54:55], v[142:143]
	v_pk_mul_f32 v[48:49], v[48:49], v[66:67] op_sel_hi:[1,0]
	v_pk_fma_f32 v[46:47], v[130:131], v[46:47], v[134:135]
	v_pk_fma_f32 v[60:61], v[148:149], v[60:61], v[152:153]
	v_cvt_pk_bf16_f32 v236, v58, v59
	v_pk_fma_f32 v[56:57], v[140:141], v[56:57], v[144:145]
	v_cvt_pk_bf16_f32 v237, v60, v61
	global_store_dwordx4 v[64:65], v[234:237], off
	v_cvt_pk_bf16_f32 v238, v54, v55
	v_cvt_pk_bf16_f32 v239, v56, v57
	v_pk_fma_f32 v[48:49], v[132:133], v[48:49], v[136:137]
	v_cvt_pk_bf16_f32 v240, v46, v47
	s_mov_b32 s4, 0x48000
	v_cvt_pk_bf16_f32 v241, v48, v49
	global_store_dwordx4 v[64:65], v[238:241], off offset:256
	ds_read_b32 v46, v0 offset:8768
	s_waitcnt lgkmcnt(0)
	v_pk_mul_f32 v[48:49], v[52:53], v[46:47] op_sel_hi:[1,0]
	v_pk_mul_f32 v[50:51], v[50:51], v[46:47] op_sel_hi:[1,0]
	v_pk_fma_f32 v[48:49], v[156:157], v[48:49], v[160:161]
	v_pk_fma_f32 v[50:51], v[154:155], v[50:51], v[158:159]
	v_pk_mul_f32 v[42:43], v[42:43], v[46:47] op_sel_hi:[1,0]
	v_cvt_pk_bf16_f32 v234, v50, v51
	v_cvt_pk_bf16_f32 v235, v48, v49
	v_add_co_u32_e32 v48, vcc, s4, v162
	v_pk_mul_f32 v[38:39], v[38:39], v[46:47] op_sel_hi:[1,0]
	v_pk_mul_f32 v[30:31], v[30:31], v[46:47] op_sel_hi:[1,0]
	v_addc_co_u32_e32 v49, vcc, 0, v163, vcc
	v_pk_mul_f32 v[44:45], v[44:45], v[46:47] op_sel_hi:[1,0]
	v_pk_fma_f32 v[42:43], v[146:147], v[42:43], v[150:151]
	v_pk_mul_f32 v[40:41], v[40:41], v[46:47] op_sel_hi:[1,0]
	v_pk_fma_f32 v[38:39], v[138:139], v[38:39], v[142:143]
	v_pk_mul_f32 v[32:33], v[32:33], v[46:47] op_sel_hi:[1,0]
	v_pk_fma_f32 v[30:31], v[130:131], v[30:31], v[134:135]
	v_pk_fma_f32 v[44:45], v[148:149], v[44:45], v[152:153]
	v_cvt_pk_bf16_f32 v236, v42, v43
	v_pk_fma_f32 v[40:41], v[140:141], v[40:41], v[144:145]
	v_cvt_pk_bf16_f32 v237, v44, v45
	global_store_dwordx4 v[48:49], v[234:237], off
	v_cvt_pk_bf16_f32 v238, v38, v39
	v_cvt_pk_bf16_f32 v239, v40, v41
	v_pk_fma_f32 v[32:33], v[132:133], v[32:33], v[136:137]
	v_cvt_pk_bf16_f32 v240, v30, v31
	s_mov_b32 s4, 0x50000
	v_cvt_pk_bf16_f32 v241, v32, v33
	global_store_dwordx4 v[48:49], v[238:241], off offset:256
	ds_read_b32 v30, v0 offset:8832
	s_waitcnt lgkmcnt(0)
	v_pk_mul_f32 v[32:33], v[36:37], v[30:31] op_sel_hi:[1,0]
	v_pk_mul_f32 v[34:35], v[34:35], v[30:31] op_sel_hi:[1,0]
	v_pk_fma_f32 v[32:33], v[156:157], v[32:33], v[160:161]
	v_pk_fma_f32 v[34:35], v[154:155], v[34:35], v[158:159]
	v_pk_mul_f32 v[26:27], v[26:27], v[30:31] op_sel_hi:[1,0]
	v_cvt_pk_bf16_f32 v234, v34, v35
	v_cvt_pk_bf16_f32 v235, v32, v33
	v_add_co_u32_e32 v32, vcc, s4, v162
	v_pk_mul_f32 v[22:23], v[22:23], v[30:31] op_sel_hi:[1,0]
	v_pk_mul_f32 v[14:15], v[14:15], v[30:31] op_sel_hi:[1,0]
	v_addc_co_u32_e32 v33, vcc, 0, v163, vcc
	v_pk_mul_f32 v[28:29], v[28:29], v[30:31] op_sel_hi:[1,0]
	v_pk_fma_f32 v[26:27], v[146:147], v[26:27], v[150:151]
	v_pk_mul_f32 v[24:25], v[24:25], v[30:31] op_sel_hi:[1,0]
	v_pk_fma_f32 v[22:23], v[138:139], v[22:23], v[142:143]
	v_pk_mul_f32 v[16:17], v[16:17], v[30:31] op_sel_hi:[1,0]
	v_pk_fma_f32 v[14:15], v[130:131], v[14:15], v[134:135]
	v_pk_fma_f32 v[28:29], v[148:149], v[28:29], v[152:153]
	v_cvt_pk_bf16_f32 v236, v26, v27
	v_pk_fma_f32 v[24:25], v[140:141], v[24:25], v[144:145]
	v_cvt_pk_bf16_f32 v237, v28, v29
	global_store_dwordx4 v[32:33], v[234:237], off
	v_cvt_pk_bf16_f32 v238, v22, v23
	v_cvt_pk_bf16_f32 v239, v24, v25
	v_pk_fma_f32 v[16:17], v[132:133], v[16:17], v[136:137]
	v_cvt_pk_bf16_f32 v240, v14, v15
	s_mov_b32 s4, 0x58000
	v_cvt_pk_bf16_f32 v241, v16, v17
	global_store_dwordx4 v[32:33], v[238:241], off offset:256
	ds_read_b32 v0, v0 offset:8896
	s_waitcnt lgkmcnt(0)
	v_pk_mul_f32 v[14:15], v[20:21], v[0:1] op_sel_hi:[1,0]
	v_pk_mul_f32 v[16:17], v[18:19], v[0:1] op_sel_hi:[1,0]
	v_pk_fma_f32 v[14:15], v[156:157], v[14:15], v[160:161]
	v_pk_fma_f32 v[16:17], v[154:155], v[16:17], v[158:159]
	v_pk_mul_f32 v[10:11], v[10:11], v[0:1] op_sel_hi:[1,0]
	v_cvt_pk_bf16_f32 v234, v16, v17
	v_cvt_pk_bf16_f32 v235, v14, v15
	v_add_co_u32_e32 v14, vcc, s4, v162
	v_pk_mul_f32 v[6:7], v[6:7], v[0:1] op_sel_hi:[1,0]
	v_pk_mul_f32 v[2:3], v[2:3], v[0:1] op_sel_hi:[1,0]
	v_addc_co_u32_e32 v15, vcc, 0, v163, vcc
	v_pk_mul_f32 v[12:13], v[12:13], v[0:1] op_sel_hi:[1,0]
	v_pk_fma_f32 v[10:11], v[146:147], v[10:11], v[150:151]
	v_pk_mul_f32 v[8:9], v[8:9], v[0:1] op_sel_hi:[1,0]
	v_pk_fma_f32 v[6:7], v[138:139], v[6:7], v[142:143]
	v_pk_mul_f32 v[4:5], v[4:5], v[0:1] op_sel_hi:[1,0]
	v_pk_fma_f32 v[2:3], v[130:131], v[2:3], v[134:135]
	v_pk_fma_f32 v[12:13], v[148:149], v[12:13], v[152:153]
	v_cvt_pk_bf16_f32 v236, v10, v11
	v_pk_fma_f32 v[8:9], v[140:141], v[8:9], v[144:145]
	v_cvt_pk_bf16_f32 v237, v12, v13
	global_store_dwordx4 v[14:15], v[234:237], off
	v_cvt_pk_bf16_f32 v238, v6, v7
	v_cvt_pk_bf16_f32 v239, v8, v9
	v_pk_fma_f32 v[4:5], v[132:133], v[4:5], v[136:137]
	v_cvt_pk_bf16_f32 v240, v2, v3
	s_nop 0
	v_cvt_pk_bf16_f32 v241, v4, v5
	global_store_dwordx4 v[14:15], v[238:241], off offset:256

.LBB0_767:
	v_readlane_b32 s4, v255, 7
	s_lshl_b32 s15, s4, 5
	v_and_or_b32 v0, v216, 31, s15
	v_lshl_add_u32 v216, s20, 8, v0
	v_lshl_add_u32 v251, v0, 2, 0
	s_and_saveexec_b64 s[4:5], s[6:7]
	s_cbranch_execz .LBB0_769
	v_readlane_b32 s16, v254, 59
	v_ashrrev_i32_e32 v217, 31, v216
	v_readlane_b32 s17, v254, 60
	s_nop 1
	v_lshl_add_u64 v[230:231], v[216:217], 4, s[16:17]
	global_load_dwordx4 v[242:245], v[230:231], off sc1
	s_mov_b32 s16, 0x800000
	s_waitcnt vmcnt(0)
	v_add_f32_e32 v0, 0, v242
	v_add_f32_e32 v0, v0, v243
	v_add_f32_e32 v0, v0, v244
	v_add_f32_e32 v0, v0, v245
	v_fmamk_f32 v0, v0, 0x3a800000, v223
	v_cmp_gt_f32_e32 vcc, s16, v0
	v_mul_f32_e32 v217, 0x4b800000, v0
	s_nop 0
	v_cndmask_b32_e32 v0, v0, v217, vcc
	v_rsq_f32_e32 v0, v0
	s_nop 0
	v_mul_f32_e32 v217, 0x45800000, v0
	v_cndmask_b32_e32 v0, v0, v217, vcc
	ds_write_b32 v251, v0 offset:8192

.LBB0_789:
	s_or_b64 exec, exec, s[4:5]
	v_readlane_b32 s4, v253, 4
	s_waitcnt lgkmcnt(0)
	v_lshl_add_u64 v[162:163], v[214:215], 0, s[24:25]
	v_readlane_b32 s5, v253, 5
	v_cvt_pk_bf16_f32 v234, v126, v127
	v_cvt_pk_bf16_f32 v235, v128, v129
	s_mov_b32 s12, 0x40001
	s_nop 0
	v_lshl_add_u64 v[162:163], v[162:163], 1, s[4:5]
	v_cvt_pk_bf16_f32 v236, v122, v123
	v_cvt_pk_bf16_f32 v237, v124, v125
	global_store_dwordx4 v[162:163], v[234:237], off
	v_cvt_pk_bf16_f32 v238, v114, v115
	v_cvt_pk_bf16_f32 v239, v116, v117
	s_mov_b32 s4, 0x8000
	v_cvt_pk_bf16_f32 v240, v106, v107
	v_cvt_pk_bf16_f32 v241, v108, v109
	global_store_dwordx4 v[162:163], v[238:241], off offset:256
	v_add_co_u32_e32 v166, vcc, s4, v162
	v_cvt_pk_bf16_f32 v234, v118, v119
	v_cvt_pk_bf16_f32 v235, v120, v121
	s_mov_b32 s4, 0x10000
	s_nop 0
	v_addc_co_u32_e32 v167, vcc, 0, v163, vcc
	v_cvt_pk_bf16_f32 v236, v110, v111
	v_cvt_pk_bf16_f32 v237, v112, v113
	global_store_dwordx4 v[166:167], v[234:237], off
	v_cvt_pk_bf16_f32 v238, v98, v99
	v_cvt_pk_bf16_f32 v239, v100, v101
	v_cvt_pk_bf16_f32 v240, v90, v91
	v_cvt_pk_bf16_f32 v241, v92, v93
	global_store_dwordx4 v[166:167], v[238:241], off offset:256
	v_add_co_u32_e32 v166, vcc, s4, v162
	v_cvt_pk_bf16_f32 v234, v102, v103
	v_cvt_pk_bf16_f32 v235, v104, v105
	s_mov_b32 s4, 0x18000
	s_nop 0
	v_addc_co_u32_e32 v167, vcc, 0, v163, vcc
	v_cvt_pk_bf16_f32 v236, v94, v95
	v_cvt_pk_bf16_f32 v237, v96, v97
	global_store_dwordx4 v[166:167], v[234:237], off
	v_cvt_pk_bf16_f32 v238, v82, v83
	v_cvt_pk_bf16_f32 v239, v84, v85
	v_cvt_pk_bf16_f32 v240, v74, v75
	v_cvt_pk_bf16_f32 v241, v76, v77
	global_store_dwordx4 v[166:167], v[238:241], off offset:256
	v_add_co_u32_e32 v166, vcc, s4, v162
	v_cvt_pk_bf16_f32 v234, v86, v87
	v_cvt_pk_bf16_f32 v235, v88, v89
	s_mov_b32 s4, 0x40000
	s_nop 0
	v_addc_co_u32_e32 v167, vcc, 0, v163, vcc
	v_cvt_pk_bf16_f32 v236, v78, v79
	v_cvt_pk_bf16_f32 v237, v80, v81
	global_store_dwordx4 v[166:167], v[234:237], off
	v_cvt_pk_bf16_f32 v238, v70, v71
	v_cvt_pk_bf16_f32 v239, v72, v73
	v_cvt_pk_bf16_f32 v240, v66, v67
	v_cvt_pk_bf16_f32 v241, v68, v69
	global_store_dwordx4 v[166:167], v[238:241], off offset:256
	v_add_co_u32_e32 v166, vcc, s4, v162
	v_cvt_pk_bf16_f32 v234, v62, v63
	v_cvt_pk_bf16_f32 v235, v64, v65
	s_mov_b32 s4, 0x48000
	s_nop 0
	v_addc_co_u32_e32 v167, vcc, 0, v163, vcc
	v_cvt_pk_bf16_f32 v236, v58, v59
	v_cvt_pk_bf16_f32 v237, v60, v61
	global_store_dwordx4 v[166:167], v[234:237], off
	v_cvt_pk_bf16_f32 v238, v54, v55
	v_cvt_pk_bf16_f32 v239, v56, v57
	v_cvt_pk_bf16_f32 v240, v50, v51
	v_cvt_pk_bf16_f32 v241, v52, v53
	global_store_dwordx4 v[166:167], v[238:241], off offset:256
	v_add_co_u32_e32 v166, vcc, s4, v162
	v_cvt_pk_bf16_f32 v234, v46, v47
	v_cvt_pk_bf16_f32 v235, v48, v49
	s_mov_b32 s4, 0x50000
	s_nop 0
	v_addc_co_u32_e32 v167, vcc, 0, v163, vcc
	v_cvt_pk_bf16_f32 v236, v42, v43
	v_cvt_pk_bf16_f32 v237, v44, v45
	global_store_dwordx4 v[166:167], v[234:237], off
	v_cvt_pk_bf16_f32 v238, v38, v39
	v_cvt_pk_bf16_f32 v239, v40, v41
	v_cvt_pk_bf16_f32 v240, v34, v35
	v_cvt_pk_bf16_f32 v241, v36, v37
	global_store_dwordx4 v[166:167], v[238:241], off offset:256
	v_add_co_u32_e32 v166, vcc, s4, v162
	v_cvt_pk_bf16_f32 v234, v30, v31
	v_cvt_pk_bf16_f32 v235, v32, v33
	s_mov_b32 s4, 0x58000
	s_nop 0
	v_addc_co_u32_e32 v167, vcc, 0, v163, vcc
	v_cvt_pk_bf16_f32 v236, v26, v27
	v_cvt_pk_bf16_f32 v237, v28, v29
	global_store_dwordx4 v[166:167], v[234:237], off
	v_cvt_pk_bf16_f32 v238, v22, v23
	v_cvt_pk_bf16_f32 v239, v24, v25
	v_cvt_pk_bf16_f32 v240, v18, v19
	v_cvt_pk_bf16_f32 v241, v20, v21
	global_store_dwordx4 v[166:167], v[238:241], off offset:256
	v_add_co_u32_e32 v162, vcc, s4, v162
	v_cvt_pk_bf16_f32 v234, v150, v151
	v_cvt_pk_bf16_f32 v235, v152, v153
	v_readlane_b32 s4, v255, 4
	s_nop 0
	v_addc_co_u32_e32 v163, vcc, 0, v163, vcc
	v_cvt_pk_bf16_f32 v236, v134, v135
	v_cvt_pk_bf16_f32 v237, v136, v137
	global_store_dwordx4 v[162:163], v[234:237], off
	v_cvt_pk_bf16_f32 v238, v14, v15
	v_cvt_pk_bf16_f32 v239, v16, v17
	v_cvt_pk_bf16_f32 v240, v2, v3
	v_cvt_pk_bf16_f32 v241, v4, v5
	global_store_dwordx4 v[162:163], v[238:241], off offset:256
	s_add_u32 s4, s4, s22
	v_readlane_b32 s5, v255, 3
	s_addc_u32 s5, s5, s23
	s_branch .LBB0_791

.LBB0_809:
	s_and_saveexec_b64 s[4:5], s[6:7]
	s_cbranch_execz .LBB0_811
	v_ashrrev_i32_e32 v217, 31, v216
	v_lshl_add_u64 v[162:163], v[216:217], 4, s[34:35]
	global_load_dwordx4 v[242:245], v[162:163], off sc1
	s_mov_b32 s6, 0x800000
	s_waitcnt vmcnt(0)
	v_add_f32_e32 v164, 0, v242
	v_add_f32_e32 v164, v164, v243
	v_add_f32_e32 v164, v164, v244
	v_add_f32_e32 v162, v164, v245
	v_fmamk_f32 v162, v162, 0x3a800000, v223
	v_cmp_gt_f32_e32 vcc, s6, v162
	v_mul_f32_e32 v163, 0x4b800000, v162
	s_nop 0
	v_cndmask_b32_e32 v162, v162, v163, vcc
	v_rsq_f32_e32 v162, v162
	s_nop 0
	v_mul_f32_e32 v163, 0x45800000, v162
	v_cndmask_b32_e32 v162, v162, v163, vcc
	ds_write_b32 v251, v162 offset:8192
.LBB0_811:
	s_or_b64 exec, exec, s[4:5]
	s_waitcnt vmcnt(0) lgkmcnt(0)
	s_barrier
	ds_read_b32 v164, v0 offset:8192
	s_lshl_b64 s[4:5], s[24:25], 1
	v_readlane_b32 s6, v254, 8
	s_add_u32 s4, s6, s4
	v_readlane_b32 s6, v254, 9
	s_addc_u32 s5, s6, s5
	s_waitcnt lgkmcnt(0)
	v_pk_mul_f32 v[126:127], v[126:127], v[164:165] op_sel_hi:[1,0]
	v_pk_mul_f32 v[122:123], v[122:123], v[164:165] op_sel_hi:[1,0]
	v_pk_mul_f32 v[114:115], v[114:115], v[164:165] op_sel_hi:[1,0]
	v_pk_mul_f32 v[106:107], v[106:107], v[164:165] op_sel_hi:[1,0]
	v_lshl_add_u64 v[162:163], v[214:215], 1, s[4:5]
	v_pk_mul_f32 v[128:129], v[128:129], v[164:165] op_sel_hi:[1,0]
	v_pk_fma_f32 v[126:127], v[154:155], v[126:127], v[158:159]
	v_pk_mul_f32 v[124:125], v[124:125], v[164:165] op_sel_hi:[1,0]
	v_pk_fma_f32 v[122:123], v[142:143], v[122:123], v[146:147]
	v_pk_mul_f32 v[116:117], v[116:117], v[164:165] op_sel_hi:[1,0]
	v_pk_fma_f32 v[114:115], v[130:131], v[114:115], v[138:139]
	v_pk_mul_f32 v[108:109], v[108:109], v[164:165] op_sel_hi:[1,0]
	v_pk_fma_f32 v[106:107], v[6:7], v[106:107], v[10:11]
	v_pk_fma_f32 v[128:129], v[156:157], v[128:129], v[160:161]
	v_cvt_pk_bf16_f32 v234, v126, v127
	v_pk_fma_f32 v[124:125], v[144:145], v[124:125], v[148:149]
	v_cvt_pk_bf16_f32 v235, v128, v129
	v_cvt_pk_bf16_f32 v236, v122, v123
	v_cvt_pk_bf16_f32 v237, v124, v125
	global_store_dwordx4 v[162:163], v[234:237], off
	v_pk_fma_f32 v[116:117], v[132:133], v[116:117], v[140:141]
	v_cvt_pk_bf16_f32 v238, v114, v115
	v_pk_fma_f32 v[108:109], v[8:9], v[108:109], v[12:13]
	v_cvt_pk_bf16_f32 v239, v116, v117
	v_cvt_pk_bf16_f32 v240, v106, v107
	v_cvt_pk_bf16_f32 v241, v108, v109
	global_store_dwordx4 v[162:163], v[238:241], off offset:256
	ds_read_b32 v106, v0 offset:8256
	s_mov_b32 s4, 0x8000
	s_waitcnt lgkmcnt(0)
	v_pk_mul_f32 v[108:109], v[120:121], v[106:107] op_sel_hi:[1,0]
	v_pk_mul_f32 v[114:115], v[118:119], v[106:107] op_sel_hi:[1,0]
	v_pk_fma_f32 v[108:109], v[156:157], v[108:109], v[160:161]
	v_pk_fma_f32 v[114:115], v[154:155], v[114:115], v[158:159]
	v_pk_mul_f32 v[110:111], v[110:111], v[106:107] op_sel_hi:[1,0]
	v_cvt_pk_bf16_f32 v234, v114, v115
	v_cvt_pk_bf16_f32 v235, v108, v109
	v_add_co_u32_e32 v108, vcc, s4, v162
	v_pk_mul_f32 v[98:99], v[98:99], v[106:107] op_sel_hi:[1,0]
	v_pk_mul_f32 v[90:91], v[90:91], v[106:107] op_sel_hi:[1,0]
	v_addc_co_u32_e32 v109, vcc, 0, v163, vcc
	v_pk_mul_f32 v[112:113], v[112:113], v[106:107] op_sel_hi:[1,0]
	v_pk_fma_f32 v[110:111], v[142:143], v[110:111], v[146:147]
	v_pk_mul_f32 v[100:101], v[100:101], v[106:107] op_sel_hi:[1,0]
	v_pk_fma_f32 v[98:99], v[130:131], v[98:99], v[138:139]
	v_pk_mul_f32 v[92:93], v[92:93], v[106:107] op_sel_hi:[1,0]
	v_pk_fma_f32 v[90:91], v[6:7], v[90:91], v[10:11]
	v_pk_fma_f32 v[112:113], v[144:145], v[112:113], v[148:149]
	v_cvt_pk_bf16_f32 v236, v110, v111
	v_pk_fma_f32 v[100:101], v[132:133], v[100:101], v[140:141]
	v_cvt_pk_bf16_f32 v237, v112, v113
	global_store_dwordx4 v[108:109], v[234:237], off
	v_cvt_pk_bf16_f32 v238, v98, v99
	v_cvt_pk_bf16_f32 v239, v100, v101
	v_pk_fma_f32 v[92:93], v[8:9], v[92:93], v[12:13]
	v_cvt_pk_bf16_f32 v240, v90, v91
	s_mov_b32 s4, 0x10000
	v_cvt_pk_bf16_f32 v241, v92, v93
	global_store_dwordx4 v[108:109], v[238:241], off offset:256
	ds_read_b32 v90, v0 offset:8320
	s_waitcnt lgkmcnt(0)
	v_pk_mul_f32 v[92:93], v[104:105], v[90:91] op_sel_hi:[1,0]
	v_pk_mul_f32 v[98:99], v[102:103], v[90:91] op_sel_hi:[1,0]
	v_pk_fma_f32 v[92:93], v[156:157], v[92:93], v[160:161]
	v_pk_fma_f32 v[98:99], v[154:155], v[98:99], v[158:159]
	v_pk_mul_f32 v[94:95], v[94:95], v[90:91] op_sel_hi:[1,0]
	v_cvt_pk_bf16_f32 v234, v98, v99
	v_cvt_pk_bf16_f32 v235, v92, v93
	v_add_co_u32_e32 v92, vcc, s4, v162
	v_pk_mul_f32 v[82:83], v[82:83], v[90:91] op_sel_hi:[1,0]
	v_pk_mul_f32 v[74:75], v[74:75], v[90:91] op_sel_hi:[1,0]
	v_addc_co_u32_e32 v93, vcc, 0, v163, vcc
	v_pk_mul_f32 v[96:97], v[96:97], v[90:91] op_sel_hi:[1,0]
	v_pk_fma_f32 v[94:95], v[142:143], v[94:95], v[146:147]
	v_pk_mul_f32 v[84:85], v[84:85], v[90:91] op_sel_hi:[1,0]
	v_pk_fma_f32 v[82:83], v[130:131], v[82:83], v[138:139]
	v_pk_mul_f32 v[76:77], v[76:77], v[90:91] op_sel_hi:[1,0]
	v_pk_fma_f32 v[74:75], v[6:7], v[74:75], v[10:11]
	v_pk_fma_f32 v[96:97], v[144:145], v[96:97], v[148:149]
	v_cvt_pk_bf16_f32 v236, v94, v95
	v_pk_fma_f32 v[84:85], v[132:133], v[84:85], v[140:141]
	v_cvt_pk_bf16_f32 v237, v96, v97
	global_store_dwordx4 v[92:93], v[234:237], off
	v_cvt_pk_bf16_f32 v238, v82, v83
	v_cvt_pk_bf16_f32 v239, v84, v85
	v_pk_fma_f32 v[76:77], v[8:9], v[76:77], v[12:13]
	v_cvt_pk_bf16_f32 v240, v74, v75
	s_mov_b32 s4, 0x18000
	v_cvt_pk_bf16_f32 v241, v76, v77
	global_store_dwordx4 v[92:93], v[238:241], off offset:256
	ds_read_b32 v74, v0 offset:8384
	s_waitcnt lgkmcnt(0)
	v_pk_mul_f32 v[76:77], v[88:89], v[74:75] op_sel_hi:[1,0]
	v_pk_mul_f32 v[82:83], v[86:87], v[74:75] op_sel_hi:[1,0]
	v_pk_fma_f32 v[76:77], v[156:157], v[76:77], v[160:161]
	v_pk_fma_f32 v[82:83], v[154:155], v[82:83], v[158:159]
	v_pk_mul_f32 v[78:79], v[78:79], v[74:75] op_sel_hi:[1,0]
	v_cvt_pk_bf16_f32 v234, v82, v83
	v_cvt_pk_bf16_f32 v235, v76, v77
	v_add_co_u32_e32 v76, vcc, s4, v162
	v_pk_mul_f32 v[70:71], v[70:71], v[74:75] op_sel_hi:[1,0]
	v_pk_mul_f32 v[66:67], v[66:67], v[74:75] op_sel_hi:[1,0]
	v_addc_co_u32_e32 v77, vcc, 0, v163, vcc
	v_pk_mul_f32 v[80:81], v[80:81], v[74:75] op_sel_hi:[1,0]
	v_pk_fma_f32 v[78:79], v[142:143], v[78:79], v[146:147]
	v_pk_mul_f32 v[72:73], v[72:73], v[74:75] op_sel_hi:[1,0]
	v_pk_fma_f32 v[70:71], v[130:131], v[70:71], v[138:139]
	v_pk_mul_f32 v[68:69], v[68:69], v[74:75] op_sel_hi:[1,0]
	v_pk_fma_f32 v[66:67], v[6:7], v[66:67], v[10:11]
	v_pk_fma_f32 v[80:81], v[144:145], v[80:81], v[148:149]
	v_cvt_pk_bf16_f32 v236, v78, v79
	v_pk_fma_f32 v[72:73], v[132:133], v[72:73], v[140:141]
	v_cvt_pk_bf16_f32 v237, v80, v81
	global_store_dwordx4 v[76:77], v[234:237], off
	v_cvt_pk_bf16_f32 v238, v70, v71
	v_cvt_pk_bf16_f32 v239, v72, v73
	v_pk_fma_f32 v[68:69], v[8:9], v[68:69], v[12:13]
	v_cvt_pk_bf16_f32 v240, v66, v67
	s_mov_b32 s4, 0x40000
	v_cvt_pk_bf16_f32 v241, v68, v69
	global_store_dwordx4 v[76:77], v[238:241], off offset:256
	ds_read_b32 v66, v0 offset:8704
	s_waitcnt lgkmcnt(0)
	v_pk_mul_f32 v[64:65], v[64:65], v[66:67] op_sel_hi:[1,0]
	v_pk_mul_f32 v[62:63], v[62:63], v[66:67] op_sel_hi:[1,0]
	v_pk_fma_f32 v[64:65], v[156:157], v[64:65], v[160:161]
	v_pk_fma_f32 v[62:63], v[154:155], v[62:63], v[158:159]
	v_pk_mul_f32 v[58:59], v[58:59], v[66:67] op_sel_hi:[1,0]
	v_cvt_pk_bf16_f32 v234, v62, v63
	v_cvt_pk_bf16_f32 v235, v64, v65
	v_add_co_u32_e32 v64, vcc, s4, v162
	v_pk_mul_f32 v[54:55], v[54:55], v[66:67] op_sel_hi:[1,0]
	v_pk_mul_f32 v[50:51], v[50:51], v[66:67] op_sel_hi:[1,0]
	v_addc_co_u32_e32 v65, vcc, 0, v163, vcc
	v_pk_mul_f32 v[60:61], v[60:61], v[66:67] op_sel_hi:[1,0]
	v_pk_fma_f32 v[58:59], v[142:143], v[58:59], v[146:147]
	v_pk_mul_f32 v[56:57], v[56:57], v[66:67] op_sel_hi:[1,0]
	v_pk_fma_f32 v[54:55], v[130:131], v[54:55], v[138:139]
	v_pk_mul_f32 v[52:53], v[52:53], v[66:67] op_sel_hi:[1,0]
	v_pk_fma_f32 v[50:51], v[6:7], v[50:51], v[10:11]
	v_pk_fma_f32 v[60:61], v[144:145], v[60:61], v[148:149]
	v_cvt_pk_bf16_f32 v236, v58, v59
	v_pk_fma_f32 v[56:57], v[132:133], v[56:57], v[140:141]
	v_cvt_pk_bf16_f32 v237, v60, v61
	global_store_dwordx4 v[64:65], v[234:237], off
	v_cvt_pk_bf16_f32 v238, v54, v55
	v_cvt_pk_bf16_f32 v239, v56, v57
	v_pk_fma_f32 v[52:53], v[8:9], v[52:53], v[12:13]
	v_cvt_pk_bf16_f32 v240, v50, v51
	s_mov_b32 s4, 0x48000
	v_cvt_pk_bf16_f32 v241, v52, v53
	global_store_dwordx4 v[64:65], v[238:241], off offset:256
	ds_read_b32 v50, v0 offset:8768
	s_waitcnt lgkmcnt(0)
	v_pk_mul_f32 v[48:49], v[48:49], v[50:51] op_sel_hi:[1,0]
	v_pk_mul_f32 v[46:47], v[46:47], v[50:51] op_sel_hi:[1,0]
	v_pk_fma_f32 v[48:49], v[156:157], v[48:49], v[160:161]
	v_pk_fma_f32 v[46:47], v[154:155], v[46:47], v[158:159]
	v_pk_mul_f32 v[42:43], v[42:43], v[50:51] op_sel_hi:[1,0]
	v_cvt_pk_bf16_f32 v234, v46, v47
	v_cvt_pk_bf16_f32 v235, v48, v49
	v_add_co_u32_e32 v48, vcc, s4, v162
	v_pk_mul_f32 v[38:39], v[38:39], v[50:51] op_sel_hi:[1,0]
	v_pk_mul_f32 v[34:35], v[34:35], v[50:51] op_sel_hi:[1,0]
	v_addc_co_u32_e32 v49, vcc, 0, v163, vcc
	v_pk_mul_f32 v[44:45], v[44:45], v[50:51] op_sel_hi:[1,0]
	v_pk_fma_f32 v[42:43], v[142:143], v[42:43], v[146:147]
	v_pk_mul_f32 v[40:41], v[40:41], v[50:51] op_sel_hi:[1,0]
	v_pk_fma_f32 v[38:39], v[130:131], v[38:39], v[138:139]
	v_pk_mul_f32 v[36:37], v[36:37], v[50:51] op_sel_hi:[1,0]
	v_pk_fma_f32 v[34:35], v[6:7], v[34:35], v[10:11]
	v_pk_fma_f32 v[44:45], v[144:145], v[44:45], v[148:149]
	v_cvt_pk_bf16_f32 v236, v42, v43
	v_pk_fma_f32 v[40:41], v[132:133], v[40:41], v[140:141]
	v_cvt_pk_bf16_f32 v237, v44, v45
	global_store_dwordx4 v[48:49], v[234:237], off
	v_cvt_pk_bf16_f32 v238, v38, v39
	v_cvt_pk_bf16_f32 v239, v40, v41
	v_pk_fma_f32 v[36:37], v[8:9], v[36:37], v[12:13]
	v_cvt_pk_bf16_f32 v240, v34, v35
	s_mov_b32 s4, 0x50000
	v_cvt_pk_bf16_f32 v241, v36, v37
	global_store_dwordx4 v[48:49], v[238:241], off offset:256
	ds_read_b32 v34, v0 offset:8832
	s_waitcnt lgkmcnt(0)
	v_pk_mul_f32 v[32:33], v[32:33], v[34:35] op_sel_hi:[1,0]
	v_pk_mul_f32 v[30:31], v[30:31], v[34:35] op_sel_hi:[1,0]
	v_pk_fma_f32 v[32:33], v[156:157], v[32:33], v[160:161]
	v_pk_fma_f32 v[30:31], v[154:155], v[30:31], v[158:159]
	v_pk_mul_f32 v[26:27], v[26:27], v[34:35] op_sel_hi:[1,0]
	v_cvt_pk_bf16_f32 v234, v30, v31
	v_cvt_pk_bf16_f32 v235, v32, v33
	v_add_co_u32_e32 v32, vcc, s4, v162
	v_pk_mul_f32 v[22:23], v[22:23], v[34:35] op_sel_hi:[1,0]
	v_pk_mul_f32 v[18:19], v[18:19], v[34:35] op_sel_hi:[1,0]
	v_addc_co_u32_e32 v33, vcc, 0, v163, vcc
	v_pk_mul_f32 v[28:29], v[28:29], v[34:35] op_sel_hi:[1,0]
	v_pk_fma_f32 v[26:27], v[142:143], v[26:27], v[146:147]
	v_pk_mul_f32 v[24:25], v[24:25], v[34:35] op_sel_hi:[1,0]
	v_pk_fma_f32 v[22:23], v[130:131], v[22:23], v[138:139]
	v_pk_mul_f32 v[20:21], v[20:21], v[34:35] op_sel_hi:[1,0]
	v_pk_fma_f32 v[18:19], v[6:7], v[18:19], v[10:11]
	v_pk_fma_f32 v[28:29], v[144:145], v[28:29], v[148:149]
	v_cvt_pk_bf16_f32 v236, v26, v27
	v_pk_fma_f32 v[24:25], v[132:133], v[24:25], v[140:141]
	v_cvt_pk_bf16_f32 v237, v28, v29
	global_store_dwordx4 v[32:33], v[234:237], off
	v_cvt_pk_bf16_f32 v238, v22, v23
	v_cvt_pk_bf16_f32 v239, v24, v25
	v_pk_fma_f32 v[20:21], v[8:9], v[20:21], v[12:13]
	v_cvt_pk_bf16_f32 v240, v18, v19
	s_mov_b32 s4, 0x58000
	v_cvt_pk_bf16_f32 v241, v20, v21
	global_store_dwordx4 v[32:33], v[238:241], off offset:256
	ds_read_b32 v0, v0 offset:8896
	s_waitcnt lgkmcnt(0)
	v_pk_mul_f32 v[18:19], v[152:153], v[0:1] op_sel_hi:[1,0]
	v_pk_mul_f32 v[20:21], v[150:151], v[0:1] op_sel_hi:[1,0]
	v_pk_fma_f32 v[18:19], v[156:157], v[18:19], v[160:161]
	v_pk_fma_f32 v[20:21], v[154:155], v[20:21], v[158:159]
	v_pk_mul_f32 v[22:23], v[134:135], v[0:1] op_sel_hi:[1,0]
	v_cvt_pk_bf16_f32 v234, v20, v21
	v_cvt_pk_bf16_f32 v235, v18, v19
	v_add_co_u32_e32 v18, vcc, s4, v162
	v_pk_mul_f32 v[14:15], v[14:15], v[0:1] op_sel_hi:[1,0]
	s_nop 0
	v_addc_co_u32_e32 v19, vcc, 0, v163, vcc
	v_pk_mul_f32 v[2:3], v[2:3], v[0:1] op_sel_hi:[1,0]
	v_pk_mul_f32 v[20:21], v[136:137], v[0:1] op_sel_hi:[1,0]
	v_pk_fma_f32 v[22:23], v[142:143], v[22:23], v[146:147]
	v_pk_mul_f32 v[16:17], v[16:17], v[0:1] op_sel_hi:[1,0]
	v_pk_fma_f32 v[14:15], v[130:131], v[14:15], v[138:139]
	v_pk_mul_f32 v[4:5], v[4:5], v[0:1] op_sel_hi:[1,0]
	v_pk_fma_f32 v[2:3], v[6:7], v[2:3], v[10:11]
	v_pk_fma_f32 v[20:21], v[144:145], v[20:21], v[148:149]
	v_cvt_pk_bf16_f32 v236, v22, v23
	v_pk_fma_f32 v[16:17], v[132:133], v[16:17], v[140:141]
	v_cvt_pk_bf16_f32 v237, v20, v21
	global_store_dwordx4 v[18:19], v[234:237], off
	v_cvt_pk_bf16_f32 v238, v14, v15
	v_cvt_pk_bf16_f32 v239, v16, v17
	v_pk_fma_f32 v[4:5], v[8:9], v[4:5], v[12:13]
	v_cvt_pk_bf16_f32 v240, v2, v3
	s_nop 0
	v_cvt_pk_bf16_f32 v241, v4, v5
	global_store_dwordx4 v[18:19], v[238:241], off offset:256

.LBB0_1051:
	s_lshl_b32 s15, s31, 5
	v_and_or_b32 v0, v216, 31, s15
	v_lshl_add_u32 v216, s16, 8, v0
	v_lshl_add_u32 v249, v0, 2, 0
	s_and_saveexec_b64 s[24:25], s[6:7]
	s_cbranch_execz .LBB0_1053
	v_ashrrev_i32_e32 v217, 31, v216
	v_lshl_add_u64 v[226:227], v[216:217], 4, s[4:5]
	global_load_dwordx4 v[242:245], v[226:227], off sc1
	s_mov_b32 s4, 0x800000
	s_waitcnt vmcnt(0)
	v_add_f32_e32 v0, 0, v242
	v_add_f32_e32 v0, v0, v243
	v_add_f32_e32 v0, v0, v244
	v_add_f32_e32 v0, v0, v245
	v_fmamk_f32 v0, v0, 0x3a800000, v223
	v_cmp_gt_f32_e32 vcc, s4, v0
	v_mul_f32_e32 v217, 0x4b800000, v0
	s_nop 0
	v_cndmask_b32_e32 v0, v0, v217, vcc
	v_rsq_f32_e32 v0, v0
	s_nop 0
	v_mul_f32_e32 v217, 0x45800000, v0
	v_cndmask_b32_e32 v0, v0, v217, vcc
	ds_write_b32 v249, v0 offset:8192

.LBB0_1073:
	s_or_b64 exec, exec, s[10:11]
	v_readlane_b32 s10, v253, 4
	s_waitcnt lgkmcnt(0)
	v_lshl_add_u64 v[162:163], v[214:215], 0, s[18:19]
	v_readlane_b32 s11, v253, 5
	v_cvt_pk_bf16_f32 v234, v126, v127
	v_cvt_pk_bf16_f32 v235, v128, v129
	s_nop 1
	v_lshl_add_u64 v[162:163], v[162:163], 1, s[10:11]
	v_cvt_pk_bf16_f32 v236, v122, v123
	v_cvt_pk_bf16_f32 v237, v124, v125
	global_store_dwordx4 v[162:163], v[234:237], off
	v_cvt_pk_bf16_f32 v238, v118, v119
	v_cvt_pk_bf16_f32 v239, v120, v121
	s_mov_b32 s10, 0x8000
	v_cvt_pk_bf16_f32 v240, v110, v111
	v_cvt_pk_bf16_f32 v241, v112, v113
	global_store_dwordx4 v[162:163], v[238:241], off offset:256
	v_add_co_u32_e32 v166, vcc, s10, v162
	v_cvt_pk_bf16_f32 v234, v114, v115
	v_cvt_pk_bf16_f32 v235, v116, v117
	s_mov_b32 s10, 0x10000
	s_nop 0
	v_addc_co_u32_e32 v167, vcc, 0, v163, vcc
	v_cvt_pk_bf16_f32 v236, v106, v107
	v_cvt_pk_bf16_f32 v237, v108, v109
	global_store_dwordx4 v[166:167], v[234:237], off
	v_cvt_pk_bf16_f32 v238, v102, v103
	v_cvt_pk_bf16_f32 v239, v104, v105
	v_cvt_pk_bf16_f32 v240, v94, v95
	v_cvt_pk_bf16_f32 v241, v96, v97
	global_store_dwordx4 v[166:167], v[238:241], off offset:256
	v_add_co_u32_e32 v166, vcc, s10, v162
	v_cvt_pk_bf16_f32 v234, v98, v99
	v_cvt_pk_bf16_f32 v235, v100, v101
	s_mov_b32 s10, 0x18000
	s_nop 0
	v_addc_co_u32_e32 v167, vcc, 0, v163, vcc
	v_cvt_pk_bf16_f32 v236, v90, v91
	v_cvt_pk_bf16_f32 v237, v92, v93
	global_store_dwordx4 v[166:167], v[234:237], off
	v_cvt_pk_bf16_f32 v238, v86, v87
	v_cvt_pk_bf16_f32 v239, v88, v89
	v_cvt_pk_bf16_f32 v240, v78, v79
	v_cvt_pk_bf16_f32 v241, v80, v81
	global_store_dwordx4 v[166:167], v[238:241], off offset:256
	v_add_co_u32_e32 v166, vcc, s10, v162
	v_cvt_pk_bf16_f32 v234, v82, v83
	v_cvt_pk_bf16_f32 v235, v84, v85
	s_mov_b32 s10, 0x40000
	s_nop 0
	v_addc_co_u32_e32 v167, vcc, 0, v163, vcc
	v_cvt_pk_bf16_f32 v236, v74, v75
	v_cvt_pk_bf16_f32 v237, v76, v77
	global_store_dwordx4 v[166:167], v[234:237], off
	v_cvt_pk_bf16_f32 v238, v70, v71
	v_cvt_pk_bf16_f32 v239, v72, v73
	v_cvt_pk_bf16_f32 v240, v66, v67
	v_cvt_pk_bf16_f32 v241, v68, v69
	global_store_dwordx4 v[166:167], v[238:241], off offset:256
	v_add_co_u32_e32 v166, vcc, s10, v162
	v_cvt_pk_bf16_f32 v234, v62, v63
	v_cvt_pk_bf16_f32 v235, v64, v65
	s_mov_b32 s10, 0x48000
	s_nop 0
	v_addc_co_u32_e32 v167, vcc, 0, v163, vcc
	v_cvt_pk_bf16_f32 v236, v58, v59
	v_cvt_pk_bf16_f32 v237, v60, v61
	global_store_dwordx4 v[166:167], v[234:237], off
	v_cvt_pk_bf16_f32 v238, v54, v55
	v_cvt_pk_bf16_f32 v239, v56, v57
	v_cvt_pk_bf16_f32 v240, v46, v47
	v_cvt_pk_bf16_f32 v241, v48, v49
	global_store_dwordx4 v[166:167], v[238:241], off offset:256
	v_add_co_u32_e32 v166, vcc, s10, v162
	v_cvt_pk_bf16_f32 v234, v50, v51
	v_cvt_pk_bf16_f32 v235, v52, v53
	s_mov_b32 s10, 0x50000
	s_nop 0
	v_addc_co_u32_e32 v167, vcc, 0, v163, vcc
	v_cvt_pk_bf16_f32 v236, v42, v43
	v_cvt_pk_bf16_f32 v237, v44, v45
	global_store_dwordx4 v[166:167], v[234:237], off
	v_cvt_pk_bf16_f32 v238, v38, v39
	v_cvt_pk_bf16_f32 v239, v40, v41
	v_cvt_pk_bf16_f32 v240, v30, v31
	v_cvt_pk_bf16_f32 v241, v32, v33
	global_store_dwordx4 v[166:167], v[238:241], off offset:256
	v_add_co_u32_e32 v166, vcc, s10, v162
	v_cvt_pk_bf16_f32 v234, v34, v35
	v_cvt_pk_bf16_f32 v235, v36, v37
	s_mov_b32 s10, 0x58000
	s_nop 0
	v_addc_co_u32_e32 v167, vcc, 0, v163, vcc
	v_cvt_pk_bf16_f32 v236, v26, v27
	v_cvt_pk_bf16_f32 v237, v28, v29
	global_store_dwordx4 v[166:167], v[234:237], off
	v_cvt_pk_bf16_f32 v238, v22, v23
	v_cvt_pk_bf16_f32 v239, v24, v25
	v_cvt_pk_bf16_f32 v240, v14, v15
	v_cvt_pk_bf16_f32 v241, v16, v17
	global_store_dwordx4 v[166:167], v[238:241], off offset:256
	v_add_co_u32_e32 v162, vcc, s10, v162
	v_cvt_pk_bf16_f32 v234, v18, v19
	v_cvt_pk_bf16_f32 v235, v20, v21
	s_add_u32 s10, s12, s20
	s_nop 0
	v_addc_co_u32_e32 v163, vcc, 0, v163, vcc
	v_cvt_pk_bf16_f32 v236, v10, v11
	v_cvt_pk_bf16_f32 v237, v12, v13
	global_store_dwordx4 v[162:163], v[234:237], off
	v_cvt_pk_bf16_f32 v238, v6, v7
	v_cvt_pk_bf16_f32 v239, v8, v9
	v_cvt_pk_bf16_f32 v240, v2, v3
	v_cvt_pk_bf16_f32 v241, v4, v5
	global_store_dwordx4 v[162:163], v[238:241], off offset:256
	s_addc_u32 s11, s14, s21
	s_mov_b32 s12, 0x40001
	s_branch .LBB0_1075

.LBB0_1093:
	s_and_saveexec_b64 s[8:9], s[6:7]
	s_cbranch_execz .LBB0_1095
	v_ashrrev_i32_e32 v217, 31, v216
	v_lshl_add_u64 v[162:163], v[216:217], 4, s[4:5]
	global_load_dwordx4 v[242:245], v[162:163], off sc1
	s_mov_b32 s4, 0x800000
	s_waitcnt vmcnt(0)
	v_add_f32_e32 v164, 0, v242
	v_add_f32_e32 v164, v164, v243
	v_add_f32_e32 v164, v164, v244
	v_add_f32_e32 v162, v164, v245
	v_fmamk_f32 v162, v162, 0x3a800000, v223
	v_cmp_gt_f32_e32 vcc, s4, v162
	v_mul_f32_e32 v163, 0x4b800000, v162
	s_nop 0
	v_cndmask_b32_e32 v162, v162, v163, vcc
	v_rsq_f32_e32 v162, v162
	s_nop 0
	v_mul_f32_e32 v163, 0x45800000, v162
	v_cndmask_b32_e32 v162, v162, v163, vcc
	ds_write_b32 v249, v162 offset:8192
.LBB0_1095:
	s_or_b64 exec, exec, s[8:9]
	s_waitcnt vmcnt(0) lgkmcnt(0)
	s_barrier
	ds_read_b32 v164, v0 offset:8192
	s_lshl_b64 s[4:5], s[18:19], 1
	v_readlane_b32 s6, v254, 8
	s_add_u32 s4, s6, s4
	v_readlane_b32 s6, v254, 9
	s_addc_u32 s5, s6, s5
	s_waitcnt lgkmcnt(0)
	v_pk_mul_f32 v[126:127], v[126:127], v[164:165] op_sel_hi:[1,0]
	v_pk_mul_f32 v[122:123], v[122:123], v[164:165] op_sel_hi:[1,0]
	v_pk_mul_f32 v[118:119], v[118:119], v[164:165] op_sel_hi:[1,0]
	v_pk_mul_f32 v[110:111], v[110:111], v[164:165] op_sel_hi:[1,0]
	v_lshl_add_u64 v[162:163], v[214:215], 1, s[4:5]
	v_pk_mul_f32 v[128:129], v[128:129], v[164:165] op_sel_hi:[1,0]
	v_pk_fma_f32 v[126:127], v[154:155], v[126:127], v[158:159]
	v_pk_mul_f32 v[124:125], v[124:125], v[164:165] op_sel_hi:[1,0]
	v_pk_fma_f32 v[122:123], v[146:147], v[122:123], v[150:151]
	v_pk_mul_f32 v[120:121], v[120:121], v[164:165] op_sel_hi:[1,0]
	v_pk_fma_f32 v[118:119], v[138:139], v[118:119], v[142:143]
	v_pk_mul_f32 v[112:113], v[112:113], v[164:165] op_sel_hi:[1,0]
	v_pk_fma_f32 v[110:111], v[130:131], v[110:111], v[134:135]
	v_pk_fma_f32 v[128:129], v[156:157], v[128:129], v[160:161]
	v_cvt_pk_bf16_f32 v234, v126, v127
	v_pk_fma_f32 v[124:125], v[148:149], v[124:125], v[152:153]
	v_cvt_pk_bf16_f32 v235, v128, v129
	v_cvt_pk_bf16_f32 v236, v122, v123
	v_cvt_pk_bf16_f32 v237, v124, v125
	global_store_dwordx4 v[162:163], v[234:237], off
	v_pk_fma_f32 v[120:121], v[140:141], v[120:121], v[144:145]
	v_cvt_pk_bf16_f32 v238, v118, v119
	v_pk_fma_f32 v[112:113], v[132:133], v[112:113], v[136:137]
	v_cvt_pk_bf16_f32 v239, v120, v121
	v_cvt_pk_bf16_f32 v240, v110, v111
	v_cvt_pk_bf16_f32 v241, v112, v113
	global_store_dwordx4 v[162:163], v[238:241], off offset:256
	ds_read_b32 v110, v0 offset:8256
	s_mov_b32 s4, 0x8000
	s_waitcnt lgkmcnt(0)
	v_pk_mul_f32 v[112:113], v[116:117], v[110:111] op_sel_hi:[1,0]
	v_pk_mul_f32 v[114:115], v[114:115], v[110:111] op_sel_hi:[1,0]
	v_pk_fma_f32 v[112:113], v[156:157], v[112:113], v[160:161]
	v_pk_fma_f32 v[114:115], v[154:155], v[114:115], v[158:159]
	v_pk_mul_f32 v[106:107], v[106:107], v[110:111] op_sel_hi:[1,0]
	v_cvt_pk_bf16_f32 v234, v114, v115
	v_cvt_pk_bf16_f32 v235, v112, v113
	v_add_co_u32_e32 v112, vcc, s4, v162
	v_pk_mul_f32 v[102:103], v[102:103], v[110:111] op_sel_hi:[1,0]
	v_pk_mul_f32 v[94:95], v[94:95], v[110:111] op_sel_hi:[1,0]
	v_addc_co_u32_e32 v113, vcc, 0, v163, vcc
	v_pk_mul_f32 v[108:109], v[108:109], v[110:111] op_sel_hi:[1,0]
	v_pk_fma_f32 v[106:107], v[146:147], v[106:107], v[150:151]
	v_pk_mul_f32 v[104:105], v[104:105], v[110:111] op_sel_hi:[1,0]
	v_pk_fma_f32 v[102:103], v[138:139], v[102:103], v[142:143]
	v_pk_mul_f32 v[96:97], v[96:97], v[110:111] op_sel_hi:[1,0]
	v_pk_fma_f32 v[94:95], v[130:131], v[94:95], v[134:135]
	v_pk_fma_f32 v[108:109], v[148:149], v[108:109], v[152:153]
	v_cvt_pk_bf16_f32 v236, v106, v107
	v_pk_fma_f32 v[104:105], v[140:141], v[104:105], v[144:145]
	v_cvt_pk_bf16_f32 v237, v108, v109
	global_store_dwordx4 v[112:113], v[234:237], off
	v_cvt_pk_bf16_f32 v238, v102, v103
	v_cvt_pk_bf16_f32 v239, v104, v105
	v_pk_fma_f32 v[96:97], v[132:133], v[96:97], v[136:137]
	v_cvt_pk_bf16_f32 v240, v94, v95
	s_mov_b32 s4, 0x10000
	v_cvt_pk_bf16_f32 v241, v96, v97
	global_store_dwordx4 v[112:113], v[238:241], off offset:256
	ds_read_b32 v94, v0 offset:8320
	s_waitcnt lgkmcnt(0)
	v_pk_mul_f32 v[96:97], v[100:101], v[94:95] op_sel_hi:[1,0]
	v_pk_mul_f32 v[98:99], v[98:99], v[94:95] op_sel_hi:[1,0]
	v_pk_fma_f32 v[96:97], v[156:157], v[96:97], v[160:161]
	v_pk_fma_f32 v[98:99], v[154:155], v[98:99], v[158:159]
	v_pk_mul_f32 v[90:91], v[90:91], v[94:95] op_sel_hi:[1,0]
	v_cvt_pk_bf16_f32 v234, v98, v99
	v_cvt_pk_bf16_f32 v235, v96, v97
	v_add_co_u32_e32 v96, vcc, s4, v162
	v_pk_mul_f32 v[86:87], v[86:87], v[94:95] op_sel_hi:[1,0]
	v_pk_mul_f32 v[78:79], v[78:79], v[94:95] op_sel_hi:[1,0]
	v_addc_co_u32_e32 v97, vcc, 0, v163, vcc
	v_pk_mul_f32 v[92:93], v[92:93], v[94:95] op_sel_hi:[1,0]
	v_pk_fma_f32 v[90:91], v[146:147], v[90:91], v[150:151]
	v_pk_mul_f32 v[88:89], v[88:89], v[94:95] op_sel_hi:[1,0]
	v_pk_fma_f32 v[86:87], v[138:139], v[86:87], v[142:143]
	v_pk_mul_f32 v[80:81], v[80:81], v[94:95] op_sel_hi:[1,0]
	v_pk_fma_f32 v[78:79], v[130:131], v[78:79], v[134:135]
	v_pk_fma_f32 v[92:93], v[148:149], v[92:93], v[152:153]
	v_cvt_pk_bf16_f32 v236, v90, v91
	v_pk_fma_f32 v[88:89], v[140:141], v[88:89], v[144:145]
	v_cvt_pk_bf16_f32 v237, v92, v93
	global_store_dwordx4 v[96:97], v[234:237], off
	v_cvt_pk_bf16_f32 v238, v86, v87
	v_cvt_pk_bf16_f32 v239, v88, v89
	v_pk_fma_f32 v[80:81], v[132:133], v[80:81], v[136:137]
	v_cvt_pk_bf16_f32 v240, v78, v79
	s_mov_b32 s4, 0x18000
	v_cvt_pk_bf16_f32 v241, v80, v81
	global_store_dwordx4 v[96:97], v[238:241], off offset:256
	ds_read_b32 v78, v0 offset:8384
	s_waitcnt lgkmcnt(0)
	v_pk_mul_f32 v[80:81], v[84:85], v[78:79] op_sel_hi:[1,0]
	v_pk_mul_f32 v[82:83], v[82:83], v[78:79] op_sel_hi:[1,0]
	v_pk_fma_f32 v[80:81], v[156:157], v[80:81], v[160:161]
	v_pk_fma_f32 v[82:83], v[154:155], v[82:83], v[158:159]
	v_pk_mul_f32 v[74:75], v[74:75], v[78:79] op_sel_hi:[1,0]
	v_cvt_pk_bf16_f32 v234, v82, v83
	v_cvt_pk_bf16_f32 v235, v80, v81
	v_add_co_u32_e32 v80, vcc, s4, v162
	v_pk_mul_f32 v[70:71], v[70:71], v[78:79] op_sel_hi:[1,0]
	v_pk_mul_f32 v[66:67], v[66:67], v[78:79] op_sel_hi:[1,0]
	v_addc_co_u32_e32 v81, vcc, 0, v163, vcc
	v_pk_mul_f32 v[76:77], v[76:77], v[78:79] op_sel_hi:[1,0]
	v_pk_fma_f32 v[74:75], v[146:147], v[74:75], v[150:151]
	v_pk_mul_f32 v[72:73], v[72:73], v[78:79] op_sel_hi:[1,0]
	v_pk_fma_f32 v[70:71], v[138:139], v[70:71], v[142:143]
	v_pk_mul_f32 v[68:69], v[68:69], v[78:79] op_sel_hi:[1,0]
	v_pk_fma_f32 v[66:67], v[130:131], v[66:67], v[134:135]
	v_pk_fma_f32 v[76:77], v[148:149], v[76:77], v[152:153]
	v_cvt_pk_bf16_f32 v236, v74, v75
	v_pk_fma_f32 v[72:73], v[140:141], v[72:73], v[144:145]
	v_cvt_pk_bf16_f32 v237, v76, v77
	global_store_dwordx4 v[80:81], v[234:237], off
	v_cvt_pk_bf16_f32 v238, v70, v71
	v_cvt_pk_bf16_f32 v239, v72, v73
	v_pk_fma_f32 v[68:69], v[132:133], v[68:69], v[136:137]
	v_cvt_pk_bf16_f32 v240, v66, v67
	s_mov_b32 s4, 0x40000
	v_cvt_pk_bf16_f32 v241, v68, v69
	global_store_dwordx4 v[80:81], v[238:241], off offset:256
	ds_read_b32 v66, v0 offset:8704
	s_waitcnt lgkmcnt(0)
	v_pk_mul_f32 v[64:65], v[64:65], v[66:67] op_sel_hi:[1,0]
	v_pk_mul_f32 v[62:63], v[62:63], v[66:67] op_sel_hi:[1,0]
	v_pk_fma_f32 v[64:65], v[156:157], v[64:65], v[160:161]
	v_pk_fma_f32 v[62:63], v[154:155], v[62:63], v[158:159]
	v_pk_mul_f32 v[58:59], v[58:59], v[66:67] op_sel_hi:[1,0]
	v_cvt_pk_bf16_f32 v234, v62, v63
	v_cvt_pk_bf16_f32 v235, v64, v65
	v_add_co_u32_e32 v64, vcc, s4, v162
	v_pk_mul_f32 v[54:55], v[54:55], v[66:67] op_sel_hi:[1,0]
	v_pk_mul_f32 v[46:47], v[46:47], v[66:67] op_sel_hi:[1,0]
	v_addc_co_u32_e32 v65, vcc, 0, v163, vcc
	v_pk_mul_f32 v[60:61], v[60:61], v[66:67] op_sel_hi:[1,0]
	v_pk_fma_f32 v[58:59], v[146:147], v[58:59], v[150:151]
	v_pk_mul_f32 v[56:57], v[56:57], v[66:67] op_sel_hi:[1,0]
	v_pk_fma_f32 v[54:55], v[138:139], v[54:55], v[142:143]
	v_pk_mul_f32 v[48:49], v[48:49], v[66:67] op_sel_hi:[1,0]
	v_pk_fma_f32 v[46:47], v[130:131], v[46:47], v[134:135]
	v_pk_fma_f32 v[60:61], v[148:149], v[60:61], v[152:153]
	v_cvt_pk_bf16_f32 v236, v58, v59
	v_pk_fma_f32 v[56:57], v[140:141], v[56:57], v[144:145]
	v_cvt_pk_bf16_f32 v237, v60, v61
	global_store_dwordx4 v[64:65], v[234:237], off
	v_cvt_pk_bf16_f32 v238, v54, v55
	v_cvt_pk_bf16_f32 v239, v56, v57
	v_pk_fma_f32 v[48:49], v[132:133], v[48:49], v[136:137]
	v_cvt_pk_bf16_f32 v240, v46, v47
	s_mov_b32 s4, 0x48000
	v_cvt_pk_bf16_f32 v241, v48, v49
	global_store_dwordx4 v[64:65], v[238:241], off offset:256
	ds_read_b32 v46, v0 offset:8768
	s_waitcnt lgkmcnt(0)
	v_pk_mul_f32 v[48:49], v[52:53], v[46:47] op_sel_hi:[1,0]
	v_pk_mul_f32 v[50:51], v[50:51], v[46:47] op_sel_hi:[1,0]
	v_pk_fma_f32 v[48:49], v[156:157], v[48:49], v[160:161]
	v_pk_fma_f32 v[50:51], v[154:155], v[50:51], v[158:159]
	v_pk_mul_f32 v[42:43], v[42:43], v[46:47] op_sel_hi:[1,0]
	v_cvt_pk_bf16_f32 v234, v50, v51
	v_cvt_pk_bf16_f32 v235, v48, v49
	v_add_co_u32_e32 v48, vcc, s4, v162
	v_pk_mul_f32 v[38:39], v[38:39], v[46:47] op_sel_hi:[1,0]
	v_pk_mul_f32 v[30:31], v[30:31], v[46:47] op_sel_hi:[1,0]
	v_addc_co_u32_e32 v49, vcc, 0, v163, vcc
	v_pk_mul_f32 v[44:45], v[44:45], v[46:47] op_sel_hi:[1,0]
	v_pk_fma_f32 v[42:43], v[146:147], v[42:43], v[150:151]
	v_pk_mul_f32 v[40:41], v[40:41], v[46:47] op_sel_hi:[1,0]
	v_pk_fma_f32 v[38:39], v[138:139], v[38:39], v[142:143]
	v_pk_mul_f32 v[32:33], v[32:33], v[46:47] op_sel_hi:[1,0]
	v_pk_fma_f32 v[30:31], v[130:131], v[30:31], v[134:135]
	v_pk_fma_f32 v[44:45], v[148:149], v[44:45], v[152:153]
	v_cvt_pk_bf16_f32 v236, v42, v43
	v_pk_fma_f32 v[40:41], v[140:141], v[40:41], v[144:145]
	v_cvt_pk_bf16_f32 v237, v44, v45
	global_store_dwordx4 v[48:49], v[234:237], off
	v_cvt_pk_bf16_f32 v238, v38, v39
	v_cvt_pk_bf16_f32 v239, v40, v41
	v_pk_fma_f32 v[32:33], v[132:133], v[32:33], v[136:137]
	v_cvt_pk_bf16_f32 v240, v30, v31
	s_mov_b32 s4, 0x50000
	v_cvt_pk_bf16_f32 v241, v32, v33
	global_store_dwordx4 v[48:49], v[238:241], off offset:256
	ds_read_b32 v30, v0 offset:8832
	s_waitcnt lgkmcnt(0)
	v_pk_mul_f32 v[32:33], v[36:37], v[30:31] op_sel_hi:[1,0]
	v_pk_mul_f32 v[34:35], v[34:35], v[30:31] op_sel_hi:[1,0]
	v_pk_fma_f32 v[32:33], v[156:157], v[32:33], v[160:161]
	v_pk_fma_f32 v[34:35], v[154:155], v[34:35], v[158:159]
	v_pk_mul_f32 v[26:27], v[26:27], v[30:31] op_sel_hi:[1,0]
	v_cvt_pk_bf16_f32 v234, v34, v35
	v_cvt_pk_bf16_f32 v235, v32, v33
	v_add_co_u32_e32 v32, vcc, s4, v162
	v_pk_mul_f32 v[22:23], v[22:23], v[30:31] op_sel_hi:[1,0]
	v_pk_mul_f32 v[14:15], v[14:15], v[30:31] op_sel_hi:[1,0]
	v_addc_co_u32_e32 v33, vcc, 0, v163, vcc
	v_pk_mul_f32 v[28:29], v[28:29], v[30:31] op_sel_hi:[1,0]
	v_pk_fma_f32 v[26:27], v[146:147], v[26:27], v[150:151]
	v_pk_mul_f32 v[24:25], v[24:25], v[30:31] op_sel_hi:[1,0]
	v_pk_fma_f32 v[22:23], v[138:139], v[22:23], v[142:143]
	v_pk_mul_f32 v[16:17], v[16:17], v[30:31] op_sel_hi:[1,0]
	v_pk_fma_f32 v[14:15], v[130:131], v[14:15], v[134:135]
	v_pk_fma_f32 v[28:29], v[148:149], v[28:29], v[152:153]
	v_cvt_pk_bf16_f32 v236, v26, v27
	v_pk_fma_f32 v[24:25], v[140:141], v[24:25], v[144:145]
	v_cvt_pk_bf16_f32 v237, v28, v29
	global_store_dwordx4 v[32:33], v[234:237], off
	v_cvt_pk_bf16_f32 v238, v22, v23
	v_cvt_pk_bf16_f32 v239, v24, v25
	v_pk_fma_f32 v[16:17], v[132:133], v[16:17], v[136:137]
	v_cvt_pk_bf16_f32 v240, v14, v15
	s_mov_b32 s4, 0x58000
	v_cvt_pk_bf16_f32 v241, v16, v17
	global_store_dwordx4 v[32:33], v[238:241], off offset:256
	ds_read_b32 v0, v0 offset:8896
	s_waitcnt lgkmcnt(0)
	v_pk_mul_f32 v[14:15], v[20:21], v[0:1] op_sel_hi:[1,0]
	v_pk_mul_f32 v[16:17], v[18:19], v[0:1] op_sel_hi:[1,0]
	v_pk_fma_f32 v[14:15], v[156:157], v[14:15], v[160:161]
	v_pk_fma_f32 v[16:17], v[154:155], v[16:17], v[158:159]
	v_pk_mul_f32 v[10:11], v[10:11], v[0:1] op_sel_hi:[1,0]
	v_cvt_pk_bf16_f32 v234, v16, v17
	v_cvt_pk_bf16_f32 v235, v14, v15
	v_add_co_u32_e32 v14, vcc, s4, v162
	v_pk_mul_f32 v[6:7], v[6:7], v[0:1] op_sel_hi:[1,0]
	v_pk_mul_f32 v[2:3], v[2:3], v[0:1] op_sel_hi:[1,0]
	v_addc_co_u32_e32 v15, vcc, 0, v163, vcc
	v_pk_mul_f32 v[12:13], v[12:13], v[0:1] op_sel_hi:[1,0]
	v_pk_fma_f32 v[10:11], v[146:147], v[10:11], v[150:151]
	v_pk_mul_f32 v[8:9], v[8:9], v[0:1] op_sel_hi:[1,0]
	v_pk_fma_f32 v[6:7], v[138:139], v[6:7], v[142:143]
	v_pk_mul_f32 v[4:5], v[4:5], v[0:1] op_sel_hi:[1,0]
	v_pk_fma_f32 v[2:3], v[130:131], v[2:3], v[134:135]
	v_pk_fma_f32 v[12:13], v[148:149], v[12:13], v[152:153]
	v_cvt_pk_bf16_f32 v236, v10, v11
	v_pk_fma_f32 v[8:9], v[140:141], v[8:9], v[144:145]
	v_cvt_pk_bf16_f32 v237, v12, v13
	global_store_dwordx4 v[14:15], v[234:237], off
	v_cvt_pk_bf16_f32 v238, v6, v7
	v_cvt_pk_bf16_f32 v239, v8, v9
	v_pk_fma_f32 v[4:5], v[132:133], v[4:5], v[136:137]
	v_cvt_pk_bf16_f32 v240, v2, v3
	s_nop 0
	v_cvt_pk_bf16_f32 v241, v4, v5
	global_store_dwordx4 v[14:15], v[238:241], off offset:256

.LBB0_1274:
	v_and_b32_e32 v0, 31, v216
	v_lshl_or_b32 v0, s12, 5, v0
	v_lshl_add_u32 v218, s10, 8, v0
	v_readlane_b32 s4, v253, 48
	v_ashrrev_i32_e32 v219, 31, v218
	v_readlane_b32 s5, v253, 49
	v_lshl_add_u32 v0, v0, 2, 0
	s_nop 0
	v_lshl_add_u64 v[218:219], v[218:219], 4, s[4:5]
	global_load_dwordx4 v[242:245], v[218:219], off sc1
	s_mov_b32 s4, 0x800000
	s_waitcnt vmcnt(0)
	v_add_f32_e32 v216, 0, v242
	v_add_f32_e32 v216, v216, v243
	v_add_f32_e32 v216, v216, v244
	v_add_f32_e32 v216, v216, v245
	v_fmamk_f32 v216, v216, 0x3a800000, v223
	v_cmp_gt_f32_e32 vcc, s4, v216
	v_mul_f32_e32 v218, 0x4b800000, v216
	s_nop 0
	v_cndmask_b32_e32 v216, v216, v218, vcc
	v_rsq_f32_e32 v216, v216
	s_nop 0
	v_mul_f32_e32 v218, 0x45800000, v216
	v_cndmask_b32_e32 v216, v216, v218, vcc
	ds_write_b32 v0, v216 offset:8192
	s_getpc_b64 s[98:99]
